# attention-gate epilogue hand-written: silu in f32 (same op sequence), wave-private LDS image, 16-byte stores along token rows
# baseline (speedup 1.0000x reference)
; #define MFMA(a, b, c) __builtin_amdgcn_mfma_f32_32x32x16_bf16((a), (b), (c), 0, 0, 0)
; template <bool AT>
; DI void gemm_main(f32x16 (&acc)[2][4], const u16* __restrict__ R, int ldr, const u16* __restrict__ Cm, int ldc,
;                   const u16* __restrict__ RT, int ldrt, int K, char* smem, int tid) {
;     ...
;       for (int i = 0; i < 4; ++i) {
;         const int cid = tid + NT * i;
;         const int row = cid >> 3, kc = cid & 7;
;         if (AT && ks1 < 8) {
;           const int kr = cid >> 5, tc = cid & 31;
;           *(u32x4*)(Rs + kr * 264 + tc * 8) = rr[i];
;         } else {
;           *(u32x4*)(Rs + row * 72 + kc * 8) = rr[i];
;         }
;         *(u32x4*)(Cs + row * 72 + kc * 8) = cr[i];
;       }
;     }
;     if (kt + 2 < nk) {
;       const int kn = kt + 2;
; #pragma unroll
;       for (int i = 0; i < 4; ++i) {
;         const int cid = tid + NT * i;
;         const int row = cid >> 3, kc = cid & 7;
;         if (AT && kn < 8) {
;           const int kr = cid >> 5, tc = cid & 31;
;           rr[i] = *(const u32x4*)(RT + (size_t)(kn * 64 + kr) * ldrt + tc * 8);
;         } else {
;           rr[i] = *(const u32x4*)(R + (size_t)row * ldr + kn * 64 + kc * 8);
;         }
;         cr[i] = *(const u32x4*)(Cm + (size_t)row * ldc + kn * 64 + kc * 8);
;       }
;     }
;     __builtin_amdgcn_sched_barrier(0x38F);
;     if (kt >= 0) {
;       const u16* Rs = S0 + (kt & 1) * STG;
;       const u16* Cs = Rs + 256 * 72;
;       const u16* RTs = Rs;
; #pragma unroll
;       for (int ks = 0; ks < 4; ++ks) {
;         bf16x8 rf[2];
; #pragma unroll
;         for (int rb = 0; rb < 2; ++rb) {
;           if (AT && kt < 8) {
;             const u16* src = RTs + (16 * ks + 8 * g) * 264 + 64 * wr + 32 * rb + li;
;             bf16x8 t;
; #pragma unroll
;             for (int j = 0; j < 8; ++j) t[j] = (short)src[j * 264];
;             rf[rb] = t;
;           } else {
;             rf[rb] = *(const bf16x8*)(Rs + (64 * wr + 32 * rb + li) * 72 + 16 * ks + 8 * g);
;           }
;         }
; #pragma unroll
;         for (int cb = 0; cb < 4; ++cb) {
;           const bf16x8 cfv = *(const bf16x8*)(Cs + (128 * wc + 32 * cb + li) * 72 + 16 * ks + 8 * g);
; #pragma unroll
;           for (int rb = 0; rb < 2; ++rb) acc[rb][cb] = MFMA(rf[rb], cfv, acc[rb][cb]);
;         }
;       }
;     }
;     __syncthreads();
.Lgt_loop:
	ds_read_b128 v[192:195], v187 offset:0
	ds_read_b128 v[220:223], v187 offset:4608
	ds_read_b128 v[232:235], v190 offset:36864
	ds_read_b128 v[236:239], v190 offset:41472
	ds_read_b128 v[240:243], v190 offset:46080
	ds_read_b128 v[244:247], v190 offset:50688
	ds_read_b128 v[224:227], v187 offset:32
	ds_read_b128 v[228:231], v187 offset:4640
	s_waitcnt lgkmcnt(5)
	v_mfma_f32_32x32x16_bf16 v[112:127], v[192:195], v[232:235], v[112:127]
	v_mfma_f32_32x32x16_bf16 v[48:63], v[220:223], v[232:235], v[48:63]
	ds_read_b128 v[232:235], v190 offset:36896
	s_waitcnt vmcnt(0)
	ds_write_b128 v191, v[144:147]
	s_waitcnt lgkmcnt(6)
	v_mfma_f32_32x32x16_bf16 v[96:111], v[192:195], v[236:239], v[96:111]
	v_mfma_f32_32x32x16_bf16 v[32:47], v[220:223], v[236:239], v[32:47]
	ds_read_b128 v[236:239], v190 offset:41504
	ds_write_b128 v191, v[152:155] offset:36864
	s_waitcnt lgkmcnt(7)
	v_mfma_f32_32x32x16_bf16 v[80:95], v[192:195], v[240:243], v[80:95]
	v_mfma_f32_32x32x16_bf16 v[16:31], v[220:223], v[240:243], v[16:31]
	ds_read_b128 v[240:243], v190 offset:46112
	ds_write_b128 v196, v[136:139]
	s_waitcnt lgkmcnt(8)
	v_mfma_f32_32x32x16_bf16 v[64:79], v[192:195], v[244:247], v[64:79]
	v_mfma_f32_32x32x16_bf16 v[0:15], v[220:223], v[244:247], v[0:15]
	ds_read_b128 v[244:247], v190 offset:50720
	ds_write_b128 v196, v[148:151] offset:36864
	ds_read_b128 v[192:195], v187 offset:64
	ds_read_b128 v[220:223], v187 offset:4672
	s_waitcnt lgkmcnt(9)
	v_mfma_f32_32x32x16_bf16 v[112:127], v[224:227], v[232:235], v[112:127]
	v_mfma_f32_32x32x16_bf16 v[48:63], v[228:231], v[232:235], v[48:63]
	ds_read_b128 v[232:235], v190 offset:36928
	ds_write_b128 v197, v[132:135]
	s_waitcnt lgkmcnt(9)
	v_mfma_f32_32x32x16_bf16 v[96:111], v[224:227], v[236:239], v[96:111]
	v_mfma_f32_32x32x16_bf16 v[32:47], v[228:231], v[236:239], v[32:47]
	ds_read_b128 v[236:239], v190 offset:41536
	ds_write_b128 v197, v[140:143] offset:36864
	s_waitcnt lgkmcnt(9)
	v_mfma_f32_32x32x16_bf16 v[80:95], v[224:227], v[240:243], v[80:95]
	v_mfma_f32_32x32x16_bf16 v[16:31], v[228:231], v[240:243], v[16:31]
	ds_read_b128 v[240:243], v190 offset:46144
	ds_write_b128 v249, v[128:131]
	s_waitcnt lgkmcnt(9)
	v_mfma_f32_32x32x16_bf16 v[64:79], v[224:227], v[244:247], v[64:79]
	v_mfma_f32_32x32x16_bf16 v[0:15], v[228:231], v[244:247], v[0:15]
	ds_read_b128 v[244:247], v190 offset:50752
	ds_write_b128 v249, v[156:159] offset:36864
	ds_read_b128 v[224:227], v187 offset:96
	ds_read_b128 v[228:231], v187 offset:4704
	s_waitcnt lgkmcnt(9)
	v_mfma_f32_32x32x16_bf16 v[112:127], v[192:195], v[232:235], v[112:127]
	v_mfma_f32_32x32x16_bf16 v[48:63], v[220:223], v[232:235], v[48:63]
	ds_read_b128 v[232:235], v190 offset:36960
	v_subrev_u32_e32 v191, 0x12000, v191
	global_load_dwordx4 v[144:147], v[174:175], off
	v_lshl_add_u64 v[174:175], v[174:175], 0, s[58:59]
	s_waitcnt lgkmcnt(8)
	v_mfma_f32_32x32x16_bf16 v[96:111], v[192:195], v[236:239], v[96:111]
	v_mfma_f32_32x32x16_bf16 v[32:47], v[220:223], v[236:239], v[32:47]
	ds_read_b128 v[236:239], v190 offset:41568
	v_subrev_u32_e32 v196, 0x12000, v196
	global_load_dwordx4 v[152:155], v[166:167], off
	v_lshl_add_u64 v[166:167], v[166:167], 0, s[58:59]
	s_waitcnt lgkmcnt(7)
	v_mfma_f32_32x32x16_bf16 v[80:95], v[192:195], v[240:243], v[80:95]
	v_mfma_f32_32x32x16_bf16 v[16:31], v[220:223], v[240:243], v[16:31]
	ds_read_b128 v[240:243], v190 offset:46176
	v_subrev_u32_e32 v197, 0x12000, v197
	global_load_dwordx4 v[136:139], v[172:173], off
	v_lshl_add_u64 v[172:173], v[172:173], 0, s[58:59]
	s_waitcnt lgkmcnt(6)
	v_mfma_f32_32x32x16_bf16 v[64:79], v[192:195], v[244:247], v[64:79]
	v_mfma_f32_32x32x16_bf16 v[0:15], v[220:223], v[244:247], v[0:15]
	ds_read_b128 v[244:247], v190 offset:50784
	v_subrev_u32_e32 v249, 0x12000, v249
	global_load_dwordx4 v[148:151], v[164:165], off
	v_lshl_add_u64 v[164:165], v[164:165], 0, s[58:59]
	v_add_u32_e32 v187, 0x12000, v187
	v_add_u32_e32 v190, 0x12000, v190
	s_waitcnt lgkmcnt(3)
	v_mfma_f32_32x32x16_bf16 v[112:127], v[224:227], v[232:235], v[112:127]
	v_mfma_f32_32x32x16_bf16 v[48:63], v[228:231], v[232:235], v[48:63]
	global_load_dwordx4 v[132:135], v[170:171], off
	v_lshl_add_u64 v[170:171], v[170:171], 0, s[58:59]
	s_waitcnt lgkmcnt(2)
	v_mfma_f32_32x32x16_bf16 v[96:111], v[224:227], v[236:239], v[96:111]
	v_mfma_f32_32x32x16_bf16 v[32:47], v[228:231], v[236:239], v[32:47]
	global_load_dwordx4 v[140:143], v[162:163], off
	v_lshl_add_u64 v[162:163], v[162:163], 0, s[58:59]
	s_waitcnt lgkmcnt(1)
	v_mfma_f32_32x32x16_bf16 v[80:95], v[224:227], v[240:243], v[80:95]
	v_mfma_f32_32x32x16_bf16 v[16:31], v[228:231], v[240:243], v[16:31]
	global_load_dwordx4 v[128:131], v[168:169], off
	v_lshl_add_u64 v[168:169], v[168:169], 0, s[58:59]
	s_waitcnt lgkmcnt(0)
	v_mfma_f32_32x32x16_bf16 v[64:79], v[224:227], v[244:247], v[64:79]
	v_mfma_f32_32x32x16_bf16 v[0:15], v[228:231], v[244:247], v[0:15]
	global_load_dwordx4 v[156:159], v[160:161], off
	v_lshl_add_u64 v[160:161], v[160:161], 0, s[58:59]
	s_waitcnt lgkmcnt(0)
	s_barrier
; #define MFMA(a, b, c) __builtin_amdgcn_mfma_f32_32x32x16_bf16((a), (b), (c), 0, 0, 0)
; template <bool AT>
; DI void gemm_main(f32x16 (&acc)[2][4], const u16* __restrict__ R, int ldr, const u16* __restrict__ Cm, int ldc,
;                   const u16* __restrict__ RT, int ldrt, int K, char* smem, int tid) {
;     ...
;       for (int i = 0; i < 4; ++i) {
;         const int cid = tid + NT * i;
;         const int row = cid >> 3, kc = cid & 7;
;         if (AT && ks1 < 8) {
;           const int kr = cid >> 5, tc = cid & 31;
;           *(u32x4*)(Rs + kr * 264 + tc * 8) = rr[i];
;         } else {
;           *(u32x4*)(Rs + row * 72 + kc * 8) = rr[i];
;         }
;         *(u32x4*)(Cs + row * 72 + kc * 8) = cr[i];
;       }
;     }
;     if (kt + 2 < nk) {
;       const int kn = kt + 2;
; #pragma unroll
;       for (int i = 0; i < 4; ++i) {
;         const int cid = tid + NT * i;
;         const int row = cid >> 3, kc = cid & 7;
;         if (AT && kn < 8) {
;           const int kr = cid >> 5, tc = cid & 31;
;           rr[i] = *(const u32x4*)(RT + (size_t)(kn * 64 + kr) * ldrt + tc * 8);
;         } else {
;           rr[i] = *(const u32x4*)(R + (size_t)row * ldr + kn * 64 + kc * 8);
;         }
;         cr[i] = *(const u32x4*)(Cm + (size_t)row * ldc + kn * 64 + kc * 8);
;       }
;     }
;     __builtin_amdgcn_sched_barrier(0x38F);
;     if (kt >= 0) {
;       const u16* Rs = S0 + (kt & 1) * STG;
;       const u16* Cs = Rs + 256 * 72;
;       const u16* RTs = Rs;
; #pragma unroll
;       for (int ks = 0; ks < 4; ++ks) {
;         bf16x8 rf[2];
; #pragma unroll
;         for (int rb = 0; rb < 2; ++rb) {
;           if (AT && kt < 8) {
;             const u16* src = RTs + (16 * ks + 8 * g) * 264 + 64 * wr + 32 * rb + li;
;             bf16x8 t;
; #pragma unroll
;             for (int j = 0; j < 8; ++j) t[j] = (short)src[j * 264];
;             rf[rb] = t;
;           } else {
;             rf[rb] = *(const bf16x8*)(Rs + (64 * wr + 32 * rb + li) * 72 + 16 * ks + 8 * g);
;           }
;         }
; #pragma unroll
;         for (int cb = 0; cb < 4; ++cb) {
;           const bf16x8 cfv = *(const bf16x8*)(Cs + (128 * wc + 32 * cb + li) * 72 + 16 * ks + 8 * g);
; #pragma unroll
;           for (int rb = 0; rb < 2; ++rb) acc[rb][cb] = MFMA(rf[rb], cfv, acc[rb][cb]);
;         }
;       }
;     }
;     __syncthreads();
	ds_read_b128 v[192:195], v187 offset:0
	ds_read_b128 v[220:223], v187 offset:4608
	ds_read_b128 v[232:235], v190 offset:36864
	ds_read_b128 v[236:239], v190 offset:41472
	ds_read_b128 v[240:243], v190 offset:46080
	ds_read_b128 v[244:247], v190 offset:50688
	ds_read_b128 v[224:227], v187 offset:32
	ds_read_b128 v[228:231], v187 offset:4640
	s_waitcnt lgkmcnt(5)
	v_mfma_f32_32x32x16_bf16 v[112:127], v[192:195], v[232:235], v[112:127]
	v_mfma_f32_32x32x16_bf16 v[48:63], v[220:223], v[232:235], v[48:63]
	ds_read_b128 v[232:235], v190 offset:36896
	s_waitcnt vmcnt(0)
	ds_write_b128 v191, v[144:147]
	s_waitcnt lgkmcnt(6)
	v_mfma_f32_32x32x16_bf16 v[96:111], v[192:195], v[236:239], v[96:111]
	v_mfma_f32_32x32x16_bf16 v[32:47], v[220:223], v[236:239], v[32:47]
	ds_read_b128 v[236:239], v190 offset:41504
	ds_write_b128 v191, v[152:155] offset:36864
	s_waitcnt lgkmcnt(7)
	v_mfma_f32_32x32x16_bf16 v[80:95], v[192:195], v[240:243], v[80:95]
	v_mfma_f32_32x32x16_bf16 v[16:31], v[220:223], v[240:243], v[16:31]
	ds_read_b128 v[240:243], v190 offset:46112
	ds_write_b128 v196, v[136:139]
	s_waitcnt lgkmcnt(8)
	v_mfma_f32_32x32x16_bf16 v[64:79], v[192:195], v[244:247], v[64:79]
	v_mfma_f32_32x32x16_bf16 v[0:15], v[220:223], v[244:247], v[0:15]
	ds_read_b128 v[244:247], v190 offset:50720
	ds_write_b128 v196, v[148:151] offset:36864
	ds_read_b128 v[192:195], v187 offset:64
	ds_read_b128 v[220:223], v187 offset:4672
	s_waitcnt lgkmcnt(9)
	v_mfma_f32_32x32x16_bf16 v[112:127], v[224:227], v[232:235], v[112:127]
	v_mfma_f32_32x32x16_bf16 v[48:63], v[228:231], v[232:235], v[48:63]
	ds_read_b128 v[232:235], v190 offset:36928
	ds_write_b128 v197, v[132:135]
	s_waitcnt lgkmcnt(9)
	v_mfma_f32_32x32x16_bf16 v[96:111], v[224:227], v[236:239], v[96:111]
	v_mfma_f32_32x32x16_bf16 v[32:47], v[228:231], v[236:239], v[32:47]
	ds_read_b128 v[236:239], v190 offset:41536
	ds_write_b128 v197, v[140:143] offset:36864
	s_waitcnt lgkmcnt(9)
	v_mfma_f32_32x32x16_bf16 v[80:95], v[224:227], v[240:243], v[80:95]
	v_mfma_f32_32x32x16_bf16 v[16:31], v[228:231], v[240:243], v[16:31]
	ds_read_b128 v[240:243], v190 offset:46144
	ds_write_b128 v249, v[128:131]
	s_waitcnt lgkmcnt(9)
	v_mfma_f32_32x32x16_bf16 v[64:79], v[224:227], v[244:247], v[64:79]
	v_mfma_f32_32x32x16_bf16 v[0:15], v[228:231], v[244:247], v[0:15]
	ds_read_b128 v[244:247], v190 offset:50752
	ds_write_b128 v249, v[156:159] offset:36864
	ds_read_b128 v[224:227], v187 offset:96
	ds_read_b128 v[228:231], v187 offset:4704
	s_waitcnt lgkmcnt(9)
	v_mfma_f32_32x32x16_bf16 v[112:127], v[192:195], v[232:235], v[112:127]
	v_mfma_f32_32x32x16_bf16 v[48:63], v[220:223], v[232:235], v[48:63]
	ds_read_b128 v[232:235], v190 offset:36960
	v_add_u32_e32 v191, 0x12000, v191
	global_load_dwordx4 v[144:147], v[174:175], off
	v_lshl_add_u64 v[174:175], v[174:175], 0, s[58:59]
	s_waitcnt lgkmcnt(8)
	v_mfma_f32_32x32x16_bf16 v[96:111], v[192:195], v[236:239], v[96:111]
	v_mfma_f32_32x32x16_bf16 v[32:47], v[220:223], v[236:239], v[32:47]
	ds_read_b128 v[236:239], v190 offset:41568
	v_add_u32_e32 v196, 0x12000, v196
	global_load_dwordx4 v[152:155], v[166:167], off
	v_lshl_add_u64 v[166:167], v[166:167], 0, s[58:59]
	s_waitcnt lgkmcnt(7)
	v_mfma_f32_32x32x16_bf16 v[80:95], v[192:195], v[240:243], v[80:95]
	v_mfma_f32_32x32x16_bf16 v[16:31], v[220:223], v[240:243], v[16:31]
	ds_read_b128 v[240:243], v190 offset:46176
	v_add_u32_e32 v197, 0x12000, v197
	global_load_dwordx4 v[136:139], v[172:173], off
	v_lshl_add_u64 v[172:173], v[172:173], 0, s[58:59]
	s_waitcnt lgkmcnt(6)
	v_mfma_f32_32x32x16_bf16 v[64:79], v[192:195], v[244:247], v[64:79]
	v_mfma_f32_32x32x16_bf16 v[0:15], v[220:223], v[244:247], v[0:15]
	ds_read_b128 v[244:247], v190 offset:50784
	v_add_u32_e32 v249, 0x12000, v249
	global_load_dwordx4 v[148:151], v[164:165], off
	v_lshl_add_u64 v[164:165], v[164:165], 0, s[58:59]
	v_subrev_u32_e32 v187, 0x12000, v187
	v_subrev_u32_e32 v190, 0x12000, v190
	s_waitcnt lgkmcnt(3)
	v_mfma_f32_32x32x16_bf16 v[112:127], v[224:227], v[232:235], v[112:127]
	v_mfma_f32_32x32x16_bf16 v[48:63], v[228:231], v[232:235], v[48:63]
	global_load_dwordx4 v[132:135], v[170:171], off
	v_lshl_add_u64 v[170:171], v[170:171], 0, s[58:59]
	s_waitcnt lgkmcnt(2)
	v_mfma_f32_32x32x16_bf16 v[96:111], v[224:227], v[236:239], v[96:111]
	v_mfma_f32_32x32x16_bf16 v[32:47], v[228:231], v[236:239], v[32:47]
	global_load_dwordx4 v[140:143], v[162:163], off
	v_lshl_add_u64 v[162:163], v[162:163], 0, s[58:59]
	s_waitcnt lgkmcnt(1)
	v_mfma_f32_32x32x16_bf16 v[80:95], v[224:227], v[240:243], v[80:95]
	v_mfma_f32_32x32x16_bf16 v[16:31], v[228:231], v[240:243], v[16:31]
	global_load_dwordx4 v[128:131], v[168:169], off
	v_lshl_add_u64 v[168:169], v[168:169], 0, s[58:59]
	s_waitcnt lgkmcnt(0)
	v_mfma_f32_32x32x16_bf16 v[64:79], v[224:227], v[244:247], v[64:79]
	v_mfma_f32_32x32x16_bf16 v[0:15], v[228:231], v[244:247], v[0:15]
	global_load_dwordx4 v[156:159], v[160:161], off
	v_lshl_add_u64 v[160:161], v[160:161], 0, s[58:59]
	s_waitcnt lgkmcnt(0)
	s_barrier
	s_add_i32 s78, s78, -1
	s_cmp_lg_u32 s78, 0
	s_cbranch_scc1 .Lgt_loop
; #define MFMA(a, b, c) __builtin_amdgcn_mfma_f32_32x32x16_bf16((a), (b), (c), 0, 0, 0)
; template <bool AT>
; DI void gemm_main(f32x16 (&acc)[2][4], const u16* __restrict__ R, int ldr, const u16* __restrict__ Cm, int ldc,
;                   const u16* __restrict__ RT, int ldrt, int K, char* smem, int tid) {
;     ...
;       for (int i = 0; i < 4; ++i) {
;         const int cid = tid + NT * i;
;         const int row = cid >> 3, kc = cid & 7;
;         if (AT && ks1 < 8) {
;           const int kr = cid >> 5, tc = cid & 31;
;           *(u32x4*)(Rs + kr * 264 + tc * 8) = rr[i];
;         } else {
;           *(u32x4*)(Rs + row * 72 + kc * 8) = rr[i];
;         }
;         *(u32x4*)(Cs + row * 72 + kc * 8) = cr[i];
;       }
;     }
;     if (kt + 2 < nk) {
;       const int kn = kt + 2;
; #pragma unroll
;       for (int i = 0; i < 4; ++i) {
;         const int cid = tid + NT * i;
;         const int row = cid >> 3, kc = cid & 7;
;         if (AT && kn < 8) {
;           const int kr = cid >> 5, tc = cid & 31;
;           rr[i] = *(const u32x4*)(RT + (size_t)(kn * 64 + kr) * ldrt + tc * 8);
;         } else {
;           rr[i] = *(const u32x4*)(R + (size_t)row * ldr + kn * 64 + kc * 8);
;         }
;         cr[i] = *(const u32x4*)(Cm + (size_t)row * ldc + kn * 64 + kc * 8);
;       }
;     }
;     __builtin_amdgcn_sched_barrier(0x38F);
;     if (kt >= 0) {
;       const u16* Rs = S0 + (kt & 1) * STG;
;       const u16* Cs = Rs + 256 * 72;
;       const u16* RTs = Rs;
; #pragma unroll
;       for (int ks = 0; ks < 4; ++ks) {
;         bf16x8 rf[2];
; #pragma unroll
;         for (int rb = 0; rb < 2; ++rb) {
;           if (AT && kt < 8) {
;             const u16* src = RTs + (16 * ks + 8 * g) * 264 + 64 * wr + 32 * rb + li;
;             bf16x8 t;
; #pragma unroll
;             for (int j = 0; j < 8; ++j) t[j] = (short)src[j * 264];
;             rf[rb] = t;
;           } else {
;             rf[rb] = *(const bf16x8*)(Rs + (64 * wr + 32 * rb + li) * 72 + 16 * ks + 8 * g);
;           }
;         }
; #pragma unroll
;         for (int cb = 0; cb < 4; ++cb) {
;           const bf16x8 cfv = *(const bf16x8*)(Cs + (128 * wc + 32 * cb + li) * 72 + 16 * ks + 8 * g);
; #pragma unroll
;           for (int rb = 0; rb < 2; ++rb) acc[rb][cb] = MFMA(rf[rb], cfv, acc[rb][cb]);
;         }
;       }
;     }
;     __syncthreads();
	ds_read_b128 v[192:195], v187 offset:0
	ds_read_b128 v[220:223], v187 offset:4608
	ds_read_b128 v[232:235], v190 offset:36864
	ds_read_b128 v[236:239], v190 offset:41472
	ds_read_b128 v[240:243], v190 offset:46080
	ds_read_b128 v[244:247], v190 offset:50688
	ds_read_b128 v[224:227], v187 offset:32
	ds_read_b128 v[228:231], v187 offset:4640
	s_waitcnt lgkmcnt(5)
	v_mfma_f32_32x32x16_bf16 v[112:127], v[192:195], v[232:235], v[112:127]
	v_mfma_f32_32x32x16_bf16 v[48:63], v[220:223], v[232:235], v[48:63]
	ds_read_b128 v[232:235], v190 offset:36896
	s_waitcnt vmcnt(0)
	ds_write_b128 v191, v[144:147]
	s_waitcnt lgkmcnt(6)
	v_mfma_f32_32x32x16_bf16 v[96:111], v[192:195], v[236:239], v[96:111]
	v_mfma_f32_32x32x16_bf16 v[32:47], v[220:223], v[236:239], v[32:47]
	ds_read_b128 v[236:239], v190 offset:41504
	ds_write_b128 v191, v[152:155] offset:36864
	s_waitcnt lgkmcnt(7)
	v_mfma_f32_32x32x16_bf16 v[80:95], v[192:195], v[240:243], v[80:95]
	v_mfma_f32_32x32x16_bf16 v[16:31], v[220:223], v[240:243], v[16:31]
	ds_read_b128 v[240:243], v190 offset:46112
	ds_write_b128 v196, v[136:139]
	s_waitcnt lgkmcnt(8)
	v_mfma_f32_32x32x16_bf16 v[64:79], v[192:195], v[244:247], v[64:79]
	v_mfma_f32_32x32x16_bf16 v[0:15], v[220:223], v[244:247], v[0:15]
	ds_read_b128 v[244:247], v190 offset:50720
	ds_write_b128 v196, v[148:151] offset:36864
	ds_read_b128 v[192:195], v187 offset:64
	ds_read_b128 v[220:223], v187 offset:4672
	s_waitcnt lgkmcnt(9)
	v_mfma_f32_32x32x16_bf16 v[112:127], v[224:227], v[232:235], v[112:127]
	v_mfma_f32_32x32x16_bf16 v[48:63], v[228:231], v[232:235], v[48:63]
	ds_read_b128 v[232:235], v190 offset:36928
	ds_write_b128 v197, v[132:135]
	s_waitcnt lgkmcnt(9)
	v_mfma_f32_32x32x16_bf16 v[96:111], v[224:227], v[236:239], v[96:111]
	v_mfma_f32_32x32x16_bf16 v[32:47], v[228:231], v[236:239], v[32:47]
	ds_read_b128 v[236:239], v190 offset:41536
	ds_write_b128 v197, v[140:143] offset:36864
	s_waitcnt lgkmcnt(9)
	v_mfma_f32_32x32x16_bf16 v[80:95], v[224:227], v[240:243], v[80:95]
	v_mfma_f32_32x32x16_bf16 v[16:31], v[228:231], v[240:243], v[16:31]
	ds_read_b128 v[240:243], v190 offset:46144
	ds_write_b128 v249, v[128:131]
	s_waitcnt lgkmcnt(9)
	v_mfma_f32_32x32x16_bf16 v[64:79], v[224:227], v[244:247], v[64:79]
	v_mfma_f32_32x32x16_bf16 v[0:15], v[228:231], v[244:247], v[0:15]
	ds_read_b128 v[244:247], v190 offset:50752
	ds_write_b128 v249, v[156:159] offset:36864
	ds_read_b128 v[224:227], v187 offset:96
	ds_read_b128 v[228:231], v187 offset:4704
	s_waitcnt lgkmcnt(9)
	v_mfma_f32_32x32x16_bf16 v[112:127], v[192:195], v[232:235], v[112:127]
	v_mfma_f32_32x32x16_bf16 v[48:63], v[220:223], v[232:235], v[48:63]
	ds_read_b128 v[232:235], v190 offset:36960
	v_subrev_u32_e32 v191, 0x12000, v191
	s_waitcnt lgkmcnt(8)
	v_mfma_f32_32x32x16_bf16 v[96:111], v[192:195], v[236:239], v[96:111]
	v_mfma_f32_32x32x16_bf16 v[32:47], v[220:223], v[236:239], v[32:47]
	ds_read_b128 v[236:239], v190 offset:41568
	v_subrev_u32_e32 v196, 0x12000, v196
	s_waitcnt lgkmcnt(7)
	v_mfma_f32_32x32x16_bf16 v[80:95], v[192:195], v[240:243], v[80:95]
	v_mfma_f32_32x32x16_bf16 v[16:31], v[220:223], v[240:243], v[16:31]
	ds_read_b128 v[240:243], v190 offset:46176
	v_subrev_u32_e32 v197, 0x12000, v197
	s_waitcnt lgkmcnt(6)
	v_mfma_f32_32x32x16_bf16 v[64:79], v[192:195], v[244:247], v[64:79]
	v_mfma_f32_32x32x16_bf16 v[0:15], v[220:223], v[244:247], v[0:15]
	ds_read_b128 v[244:247], v190 offset:50784
	v_subrev_u32_e32 v249, 0x12000, v249
	v_add_u32_e32 v187, 0x12000, v187
	v_add_u32_e32 v190, 0x12000, v190
	s_waitcnt lgkmcnt(3)
	v_mfma_f32_32x32x16_bf16 v[112:127], v[224:227], v[232:235], v[112:127]
	v_mfma_f32_32x32x16_bf16 v[48:63], v[228:231], v[232:235], v[48:63]
	s_waitcnt lgkmcnt(2)
	v_mfma_f32_32x32x16_bf16 v[96:111], v[224:227], v[236:239], v[96:111]
	v_mfma_f32_32x32x16_bf16 v[32:47], v[228:231], v[236:239], v[32:47]
	s_waitcnt lgkmcnt(1)
	v_mfma_f32_32x32x16_bf16 v[80:95], v[224:227], v[240:243], v[80:95]
	v_mfma_f32_32x32x16_bf16 v[16:31], v[228:231], v[240:243], v[16:31]
	s_waitcnt lgkmcnt(0)
	v_mfma_f32_32x32x16_bf16 v[64:79], v[224:227], v[244:247], v[64:79]
	v_mfma_f32_32x32x16_bf16 v[0:15], v[228:231], v[244:247], v[0:15]
	s_waitcnt lgkmcnt(0)
	s_barrier
	ds_read_b128 v[192:195], v187 offset:0
	ds_read_b128 v[220:223], v187 offset:4608
	ds_read_b128 v[232:235], v190 offset:36864
	ds_read_b128 v[236:239], v190 offset:41472
	ds_read_b128 v[240:243], v190 offset:46080
	ds_read_b128 v[244:247], v190 offset:50688
	ds_read_b128 v[224:227], v187 offset:32
	ds_read_b128 v[228:231], v187 offset:4640
	s_waitcnt lgkmcnt(5)
	v_mfma_f32_32x32x16_bf16 v[112:127], v[192:195], v[232:235], v[112:127]
	v_mfma_f32_32x32x16_bf16 v[48:63], v[220:223], v[232:235], v[48:63]
	ds_read_b128 v[232:235], v190 offset:36896
	s_waitcnt lgkmcnt(5)
	v_mfma_f32_32x32x16_bf16 v[96:111], v[192:195], v[236:239], v[96:111]
	v_mfma_f32_32x32x16_bf16 v[32:47], v[220:223], v[236:239], v[32:47]
	ds_read_b128 v[236:239], v190 offset:41504
	s_waitcnt lgkmcnt(5)
	v_mfma_f32_32x32x16_bf16 v[80:95], v[192:195], v[240:243], v[80:95]
	v_mfma_f32_32x32x16_bf16 v[16:31], v[220:223], v[240:243], v[16:31]
	ds_read_b128 v[240:243], v190 offset:46112
	s_waitcnt lgkmcnt(5)
	v_mfma_f32_32x32x16_bf16 v[64:79], v[192:195], v[244:247], v[64:79]
	v_mfma_f32_32x32x16_bf16 v[0:15], v[220:223], v[244:247], v[0:15]
	ds_read_b128 v[244:247], v190 offset:50720
	ds_read_b128 v[192:195], v187 offset:64
	ds_read_b128 v[220:223], v187 offset:4672
	s_waitcnt lgkmcnt(5)
	v_mfma_f32_32x32x16_bf16 v[112:127], v[224:227], v[232:235], v[112:127]
	v_mfma_f32_32x32x16_bf16 v[48:63], v[228:231], v[232:235], v[48:63]
	ds_read_b128 v[232:235], v190 offset:36928
	s_waitcnt lgkmcnt(5)
; #define MFMA(a, b, c) __builtin_amdgcn_mfma_f32_32x32x16_bf16((a), (b), (c), 0, 0, 0)
; DI u16 f2bf(float a) { return (u16)(pack2(a, 0.f) & 0xffffu); }
; DI int crow(int reg, int g) { return (reg & 3) + 8 * (reg >> 2) + 4 * g; }
; DI float siluf(float x) { return x * __builtin_amdgcn_rcpf(1.f + __expf(-x)); }
; template <bool AT>
; DI void gemm_main(f32x16 (&acc)[2][4], const u16* __restrict__ R, int ldr, const u16* __restrict__ Cm, int ldc,
;                   const u16* __restrict__ RT, int ldrt, int K, char* smem, int tid) {
;     ...
;       for (int ks = 0; ks < 4; ++ks) {
;         bf16x8 rf[2];
; #pragma unroll
;         for (int rb = 0; rb < 2; ++rb) {
;           if (AT && kt < 8) {
;             const u16* src = RTs + (16 * ks + 8 * g) * 264 + 64 * wr + 32 * rb + li;
;             bf16x8 t;
; #pragma unroll
;             for (int j = 0; j < 8; ++j) t[j] = (short)src[j * 264];
;             rf[rb] = t;
;           } else {
;             rf[rb] = *(const bf16x8*)(Rs + (64 * wr + 32 * rb + li) * 72 + 16 * ks + 8 * g);
;           }
;         }
; #pragma unroll
;         for (int cb = 0; cb < 4; ++cb) {
;           const bf16x8 cfv = *(const bf16x8*)(Cs + (128 * wc + 32 * cb + li) * 72 + 16 * ks + 8 * g);
; #pragma unroll
;           for (int rb = 0; rb < 2; ++rb) acc[rb][cb] = MFMA(rf[rb], cfv, acc[rb][cb]);
;         }
;       }
;     }
;     __syncthreads();
; template <bool TR>
; DI void gemm_in_tile(const P& p, int l, int id, char* smem) {
;     ...
; #pragma unroll
;     for (int rb = 0; rb < 2; ++rb) {
; #pragma unroll
;       for (int reg = 0; reg < 16; ++reg) {
;         if ((reg & 7) == 0) asm volatile("" ::: "memory");
;         const int rl = 64 * wr + 32 * rb + crow(reg, g);
;         const int tok = m0 + rl;
;         const float rs = rs_s[rl];
; #pragma unroll
;         for (int cb = 0; cb < 4; ++cb) {
;           const int col = n0 - 3584 + 128 * wc + 32 * cb + li;
;           p.AG[(size_t)tok * 512 + col] = f2bf(siluf(acc[rb][cb][reg] * rs));
	v_mfma_f32_32x32x16_bf16 v[96:111], v[224:227], v[236:239], v[96:111]
	v_mfma_f32_32x32x16_bf16 v[32:47], v[228:231], v[236:239], v[32:47]
	ds_read_b128 v[236:239], v190 offset:41536
	s_waitcnt lgkmcnt(5)
	v_mfma_f32_32x32x16_bf16 v[80:95], v[224:227], v[240:243], v[80:95]
	v_mfma_f32_32x32x16_bf16 v[16:31], v[228:231], v[240:243], v[16:31]
	ds_read_b128 v[240:243], v190 offset:46144
	s_waitcnt lgkmcnt(5)
	v_mfma_f32_32x32x16_bf16 v[64:79], v[224:227], v[244:247], v[64:79]
	v_mfma_f32_32x32x16_bf16 v[0:15], v[228:231], v[244:247], v[0:15]
	ds_read_b128 v[244:247], v190 offset:50752
	ds_read_b128 v[224:227], v187 offset:96
	ds_read_b128 v[228:231], v187 offset:4704
	s_waitcnt lgkmcnt(5)
	v_mfma_f32_32x32x16_bf16 v[112:127], v[192:195], v[232:235], v[112:127]
	v_mfma_f32_32x32x16_bf16 v[48:63], v[220:223], v[232:235], v[48:63]
	ds_read_b128 v[232:235], v190 offset:36960
	v_add_u32_e32 v191, 0x12000, v191
	s_waitcnt lgkmcnt(5)
	v_mfma_f32_32x32x16_bf16 v[96:111], v[192:195], v[236:239], v[96:111]
	v_mfma_f32_32x32x16_bf16 v[32:47], v[220:223], v[236:239], v[32:47]
	ds_read_b128 v[236:239], v190 offset:41568
	v_add_u32_e32 v196, 0x12000, v196
	s_waitcnt lgkmcnt(5)
	v_mfma_f32_32x32x16_bf16 v[80:95], v[192:195], v[240:243], v[80:95]
	v_mfma_f32_32x32x16_bf16 v[16:31], v[220:223], v[240:243], v[16:31]
	ds_read_b128 v[240:243], v190 offset:46176
	v_add_u32_e32 v197, 0x12000, v197
	s_waitcnt lgkmcnt(5)
	v_mfma_f32_32x32x16_bf16 v[64:79], v[192:195], v[244:247], v[64:79]
	v_mfma_f32_32x32x16_bf16 v[0:15], v[220:223], v[244:247], v[0:15]
	ds_read_b128 v[244:247], v190 offset:50784
	v_add_u32_e32 v249, 0x12000, v249
	v_subrev_u32_e32 v187, 0x12000, v187
	v_subrev_u32_e32 v190, 0x12000, v190
	s_waitcnt lgkmcnt(3)
	v_mfma_f32_32x32x16_bf16 v[112:127], v[224:227], v[232:235], v[112:127]
	v_mfma_f32_32x32x16_bf16 v[48:63], v[228:231], v[232:235], v[48:63]
	s_waitcnt lgkmcnt(2)
	v_mfma_f32_32x32x16_bf16 v[96:111], v[224:227], v[236:239], v[96:111]
	v_mfma_f32_32x32x16_bf16 v[32:47], v[228:231], v[236:239], v[32:47]
	s_waitcnt lgkmcnt(1)
	v_mfma_f32_32x32x16_bf16 v[80:95], v[224:227], v[240:243], v[80:95]
	v_mfma_f32_32x32x16_bf16 v[16:31], v[228:231], v[240:243], v[16:31]
	s_waitcnt lgkmcnt(0)
	v_mfma_f32_32x32x16_bf16 v[64:79], v[224:227], v[244:247], v[64:79]
	v_mfma_f32_32x32x16_bf16 v[0:15], v[228:231], v[244:247], v[0:15]
	s_waitcnt lgkmcnt(0)
	s_barrier
	s_nop 7
	v_bfe_u32 v145, v176, 6, 1
	s_mov_b64 s[8:9], -1
	v_ashrrev_i32_e32 v140, 7, v176
	v_bfe_u32 v141, v176, 5, 1
	v_lshlrev_b32_e32 v128, 6, v140
	v_lshl_or_b32 v144, v141, 2, v128
	s_cmp_lt_u32 s11, 12
	s_cbranch_scc1 .LBB0_332
	s_add_i32 s8, s56, 0xfffff200
	v_lshlrev_b32_e32 v128, 7, v145
	v_or3_b32 v132, v128, s8, v177
	s_add_i32 s8, 0, 0x24000
	v_lshl_add_u32 v196, v144, 2, s8
	v_add_u32_e32 v140, s76, v144
	v_and_b32_e32 v251, 63, v198
	v_lshrrev_b32_e32 v133, 6, v198
	v_lshlrev_b32_e32 v133, 14, v133
	v_lshrrev_b32_e32 v134, 5, v251
	v_lshlrev_b32_e32 v134, 10, v134
	v_and_b32_e32 v135, 31, v251
	v_lshl_add_u32 v134, v135, 1, v134
	v_add_u32_e32 v197, v134, v133
	v_lshrrev_b32_e32 v134, 4, v251
	v_and_b32_e32 v135, 15, v251
	v_lshlrev_b32_e32 v136, 8, v134
	v_lshl_add_u32 v136, v135, 4, v136
	v_add_u32_e32 v249, v136, v133
	v_and_b32_e32 v140, 0xfffffffb, v140
	v_add_u32_e32 v140, v140, v134
	v_lshlrev_b32_e32 v140, 10, v140
	v_and_b32_e32 v132, 0xffffffe0, v132
	v_lshl_add_u32 v140, v132, 1, v140
	v_lshl_add_u32 v250, v135, 4, v140
	ds_read_b128 v[128:131], v196 offset:0
	s_waitcnt lgkmcnt(0)
	v_mul_f32_e32 v112, v112, v128
	v_mul_f32_e32 v96, v96, v128
	v_mul_f32_e32 v132, 0xbfb8aa3b, v112
	v_mul_f32_e32 v133, 0xbfb8aa3b, v96
	v_exp_f32_e32 v132, v132
	v_exp_f32_e32 v133, v133
	v_add_f32_e32 v132, 1.0, v132
	v_add_f32_e32 v133, 1.0, v133
	v_rcp_f32_e32 v132, v132
	v_rcp_f32_e32 v133, v133
	v_mul_f32_e32 v112, v112, v132
	v_mul_f32_e32 v96, v96, v133
	v_cvt_pk_bf16_f32 v134, v112, v96
	ds_write_b16 v197, v134 offset:0
	ds_write_b16_d16_hi v197, v134 offset:64
	v_mul_f32_e32 v80, v80, v128
	v_mul_f32_e32 v64, v64, v128
	v_mul_f32_e32 v136, 0xbfb8aa3b, v80
	v_mul_f32_e32 v137, 0xbfb8aa3b, v64
	v_exp_f32_e32 v136, v136
	v_exp_f32_e32 v137, v137
	v_add_f32_e32 v136, 1.0, v136
	v_add_f32_e32 v137, 1.0, v137
	v_rcp_f32_e32 v136, v136
	v_rcp_f32_e32 v137, v137
	v_mul_f32_e32 v80, v80, v136
	v_mul_f32_e32 v64, v64, v137
	v_cvt_pk_bf16_f32 v138, v80, v64
	ds_write_b16 v197, v138 offset:128
	ds_write_b16_d16_hi v197, v138 offset:192
	v_mul_f32_e32 v113, v113, v129
	v_mul_f32_e32 v97, v97, v129
	v_mul_f32_e32 v132, 0xbfb8aa3b, v113
	v_mul_f32_e32 v133, 0xbfb8aa3b, v97
	v_exp_f32_e32 v132, v132
	v_exp_f32_e32 v133, v133
	v_add_f32_e32 v132, 1.0, v132
	v_add_f32_e32 v133, 1.0, v133
	v_rcp_f32_e32 v132, v132
	v_rcp_f32_e32 v133, v133
	v_mul_f32_e32 v113, v113, v132
	v_mul_f32_e32 v97, v97, v133
	v_cvt_pk_bf16_f32 v134, v113, v97
	ds_write_b16 v197, v134 offset:256
	ds_write_b16_d16_hi v197, v134 offset:320
	v_mul_f32_e32 v81, v81, v129
	v_mul_f32_e32 v65, v65, v129
	v_mul_f32_e32 v136, 0xbfb8aa3b, v81
	v_mul_f32_e32 v137, 0xbfb8aa3b, v65
	v_exp_f32_e32 v136, v136
	v_exp_f32_e32 v137, v137
	v_add_f32_e32 v136, 1.0, v136
	v_add_f32_e32 v137, 1.0, v137
	v_rcp_f32_e32 v136, v136
	v_rcp_f32_e32 v137, v137
	v_mul_f32_e32 v81, v81, v136
	v_mul_f32_e32 v65, v65, v137
	v_cvt_pk_bf16_f32 v138, v81, v65
	ds_write_b16 v197, v138 offset:384
	ds_write_b16_d16_hi v197, v138 offset:448
	v_mul_f32_e32 v114, v114, v130
	v_mul_f32_e32 v98, v98, v130
	v_mul_f32_e32 v132, 0xbfb8aa3b, v114
	v_mul_f32_e32 v133, 0xbfb8aa3b, v98
	v_exp_f32_e32 v132, v132
	v_exp_f32_e32 v133, v133
	v_add_f32_e32 v132, 1.0, v132
; DI u16 f2bf(float a) { return (u16)(pack2(a, 0.f) & 0xffffu); }
; DI int crow(int reg, int g) { return (reg & 3) + 8 * (reg >> 2) + 4 * g; }
; DI float siluf(float x) { return x * __builtin_amdgcn_rcpf(1.f + __expf(-x)); }
; template <bool TR>
; DI void gemm_in_tile(const P& p, int l, int id, char* smem) {
;     ...
; #pragma unroll
;     for (int rb = 0; rb < 2; ++rb) {
; #pragma unroll
;       for (int reg = 0; reg < 16; ++reg) {
;         if ((reg & 7) == 0) asm volatile("" ::: "memory");
;         const int rl = 64 * wr + 32 * rb + crow(reg, g);
;         const int tok = m0 + rl;
;         const float rs = rs_s[rl];
; #pragma unroll
;         for (int cb = 0; cb < 4; ++cb) {
;           const int col = n0 - 3584 + 128 * wc + 32 * cb + li;
;           p.AG[(size_t)tok * 512 + col] = f2bf(siluf(acc[rb][cb][reg] * rs));
	v_add_f32_e32 v133, 1.0, v133
	v_rcp_f32_e32 v132, v132
	v_rcp_f32_e32 v133, v133
	v_mul_f32_e32 v114, v114, v132
	v_mul_f32_e32 v98, v98, v133
	v_cvt_pk_bf16_f32 v134, v114, v98
	ds_write_b16 v197, v134 offset:512
	ds_write_b16_d16_hi v197, v134 offset:576
	v_mul_f32_e32 v82, v82, v130
	v_mul_f32_e32 v66, v66, v130
	v_mul_f32_e32 v136, 0xbfb8aa3b, v82
	v_mul_f32_e32 v137, 0xbfb8aa3b, v66
	v_exp_f32_e32 v136, v136
	v_exp_f32_e32 v137, v137
	v_add_f32_e32 v136, 1.0, v136
	v_add_f32_e32 v137, 1.0, v137
	v_rcp_f32_e32 v136, v136
	v_rcp_f32_e32 v137, v137
	v_mul_f32_e32 v82, v82, v136
	v_mul_f32_e32 v66, v66, v137
	v_cvt_pk_bf16_f32 v138, v82, v66
	ds_write_b16 v197, v138 offset:640
	ds_write_b16_d16_hi v197, v138 offset:704
	v_mul_f32_e32 v115, v115, v131
	v_mul_f32_e32 v99, v99, v131
	v_mul_f32_e32 v132, 0xbfb8aa3b, v115
	v_mul_f32_e32 v133, 0xbfb8aa3b, v99
	v_exp_f32_e32 v132, v132
	v_exp_f32_e32 v133, v133
	v_add_f32_e32 v132, 1.0, v132
	v_add_f32_e32 v133, 1.0, v133
	v_rcp_f32_e32 v132, v132
	v_rcp_f32_e32 v133, v133
	v_mul_f32_e32 v115, v115, v132
	v_mul_f32_e32 v99, v99, v133
	v_cvt_pk_bf16_f32 v134, v115, v99
	ds_write_b16 v197, v134 offset:768
	ds_write_b16_d16_hi v197, v134 offset:832
	v_mul_f32_e32 v83, v83, v131
	v_mul_f32_e32 v67, v67, v131
	v_mul_f32_e32 v136, 0xbfb8aa3b, v83
	v_mul_f32_e32 v137, 0xbfb8aa3b, v67
	v_exp_f32_e32 v136, v136
	v_exp_f32_e32 v137, v137
	v_add_f32_e32 v136, 1.0, v136
	v_add_f32_e32 v137, 1.0, v137
	v_rcp_f32_e32 v136, v136
	v_rcp_f32_e32 v137, v137
	v_mul_f32_e32 v83, v83, v136
	v_mul_f32_e32 v67, v67, v137
	v_cvt_pk_bf16_f32 v138, v83, v67
	ds_write_b16 v197, v138 offset:896
	ds_write_b16_d16_hi v197, v138 offset:960
	ds_read_b128 v[128:131], v196 offset:32
	s_waitcnt lgkmcnt(0)
	v_mul_f32_e32 v116, v116, v128
	v_mul_f32_e32 v100, v100, v128
	v_mul_f32_e32 v132, 0xbfb8aa3b, v116
	v_mul_f32_e32 v133, 0xbfb8aa3b, v100
	v_exp_f32_e32 v132, v132
	v_exp_f32_e32 v133, v133
	v_add_f32_e32 v132, 1.0, v132
	v_add_f32_e32 v133, 1.0, v133
	v_rcp_f32_e32 v132, v132
	v_rcp_f32_e32 v133, v133
	v_mul_f32_e32 v116, v116, v132
	v_mul_f32_e32 v100, v100, v133
	v_cvt_pk_bf16_f32 v134, v116, v100
	ds_write_b16 v197, v134 offset:2048
	ds_write_b16_d16_hi v197, v134 offset:2112
	v_mul_f32_e32 v84, v84, v128
	v_mul_f32_e32 v68, v68, v128
	v_mul_f32_e32 v136, 0xbfb8aa3b, v84
	v_mul_f32_e32 v137, 0xbfb8aa3b, v68
	v_exp_f32_e32 v136, v136
	v_exp_f32_e32 v137, v137
	v_add_f32_e32 v136, 1.0, v136
	v_add_f32_e32 v137, 1.0, v137
	v_rcp_f32_e32 v136, v136
	v_rcp_f32_e32 v137, v137
	v_mul_f32_e32 v84, v84, v136
	v_mul_f32_e32 v68, v68, v137
	v_cvt_pk_bf16_f32 v138, v84, v68
	ds_write_b16 v197, v138 offset:2176
	ds_write_b16_d16_hi v197, v138 offset:2240
	v_mul_f32_e32 v117, v117, v129
	v_mul_f32_e32 v101, v101, v129
	v_mul_f32_e32 v132, 0xbfb8aa3b, v117
	v_mul_f32_e32 v133, 0xbfb8aa3b, v101
	v_exp_f32_e32 v132, v132
	v_exp_f32_e32 v133, v133
	v_add_f32_e32 v132, 1.0, v132
	v_add_f32_e32 v133, 1.0, v133
	v_rcp_f32_e32 v132, v132
	v_rcp_f32_e32 v133, v133
	v_mul_f32_e32 v117, v117, v132
	v_mul_f32_e32 v101, v101, v133
	v_cvt_pk_bf16_f32 v134, v117, v101
	ds_write_b16 v197, v134 offset:2304
	ds_write_b16_d16_hi v197, v134 offset:2368
	v_mul_f32_e32 v85, v85, v129
	v_mul_f32_e32 v69, v69, v129
	v_mul_f32_e32 v136, 0xbfb8aa3b, v85
	v_mul_f32_e32 v137, 0xbfb8aa3b, v69
	v_exp_f32_e32 v136, v136
	v_exp_f32_e32 v137, v137
	v_add_f32_e32 v136, 1.0, v136
	v_add_f32_e32 v137, 1.0, v137
	v_rcp_f32_e32 v136, v136
	v_rcp_f32_e32 v137, v137
	v_mul_f32_e32 v85, v85, v136
	v_mul_f32_e32 v69, v69, v137
	v_cvt_pk_bf16_f32 v138, v85, v69
	ds_write_b16 v197, v138 offset:2432
	ds_write_b16_d16_hi v197, v138 offset:2496
	v_mul_f32_e32 v118, v118, v130
	v_mul_f32_e32 v102, v102, v130
	v_mul_f32_e32 v132, 0xbfb8aa3b, v118
	v_mul_f32_e32 v133, 0xbfb8aa3b, v102
	v_exp_f32_e32 v132, v132
	v_exp_f32_e32 v133, v133
	v_add_f32_e32 v132, 1.0, v132
	v_add_f32_e32 v133, 1.0, v133
	v_rcp_f32_e32 v132, v132
	v_rcp_f32_e32 v133, v133
	v_mul_f32_e32 v118, v118, v132
	v_mul_f32_e32 v102, v102, v133
	v_cvt_pk_bf16_f32 v134, v118, v102
	ds_write_b16 v197, v134 offset:2560
	ds_write_b16_d16_hi v197, v134 offset:2624
	v_mul_f32_e32 v86, v86, v130
	v_mul_f32_e32 v70, v70, v130
	v_mul_f32_e32 v136, 0xbfb8aa3b, v86
	v_mul_f32_e32 v137, 0xbfb8aa3b, v70
	v_exp_f32_e32 v136, v136
	v_exp_f32_e32 v137, v137
	v_add_f32_e32 v136, 1.0, v136
	v_add_f32_e32 v137, 1.0, v137
	v_rcp_f32_e32 v136, v136
	v_rcp_f32_e32 v137, v137
	v_mul_f32_e32 v86, v86, v136
	v_mul_f32_e32 v70, v70, v137
	v_cvt_pk_bf16_f32 v138, v86, v70
	ds_write_b16 v197, v138 offset:2688
	ds_write_b16_d16_hi v197, v138 offset:2752
	v_mul_f32_e32 v119, v119, v131
	v_mul_f32_e32 v103, v103, v131
	v_mul_f32_e32 v132, 0xbfb8aa3b, v119
	v_mul_f32_e32 v133, 0xbfb8aa3b, v103
	v_exp_f32_e32 v132, v132
	v_exp_f32_e32 v133, v133
	v_add_f32_e32 v132, 1.0, v132
	v_add_f32_e32 v133, 1.0, v133
	v_rcp_f32_e32 v132, v132
	v_rcp_f32_e32 v133, v133
	v_mul_f32_e32 v119, v119, v132
	v_mul_f32_e32 v103, v103, v133
	v_cvt_pk_bf16_f32 v134, v119, v103
	ds_write_b16 v197, v134 offset:2816
	ds_write_b16_d16_hi v197, v134 offset:2880
	v_mul_f32_e32 v87, v87, v131
	v_mul_f32_e32 v71, v71, v131
	v_mul_f32_e32 v136, 0xbfb8aa3b, v87
	v_mul_f32_e32 v137, 0xbfb8aa3b, v71
	v_exp_f32_e32 v136, v136
	v_exp_f32_e32 v137, v137
	v_add_f32_e32 v136, 1.0, v136
	v_add_f32_e32 v137, 1.0, v137
	v_rcp_f32_e32 v136, v136
	v_rcp_f32_e32 v137, v137
	v_mul_f32_e32 v87, v87, v136
	v_mul_f32_e32 v71, v71, v137
	v_cvt_pk_bf16_f32 v138, v87, v71
	ds_write_b16 v197, v138 offset:2944
	ds_write_b16_d16_hi v197, v138 offset:3008
	ds_read_b128 v[128:131], v196 offset:64
	s_waitcnt lgkmcnt(0)
; DI u16 f2bf(float a) { return (u16)(pack2(a, 0.f) & 0xffffu); }
; DI int crow(int reg, int g) { return (reg & 3) + 8 * (reg >> 2) + 4 * g; }
; DI float siluf(float x) { return x * __builtin_amdgcn_rcpf(1.f + __expf(-x)); }
; template <bool TR>
; DI void gemm_in_tile(const P& p, int l, int id, char* smem) {
;     ...
; #pragma unroll
;     for (int rb = 0; rb < 2; ++rb) {
; #pragma unroll
;       for (int reg = 0; reg < 16; ++reg) {
;         if ((reg & 7) == 0) asm volatile("" ::: "memory");
;         const int rl = 64 * wr + 32 * rb + crow(reg, g);
;         const int tok = m0 + rl;
;         const float rs = rs_s[rl];
; #pragma unroll
;         for (int cb = 0; cb < 4; ++cb) {
;           const int col = n0 - 3584 + 128 * wc + 32 * cb + li;
;           p.AG[(size_t)tok * 512 + col] = f2bf(siluf(acc[rb][cb][reg] * rs));
	v_mul_f32_e32 v120, v120, v128
	v_mul_f32_e32 v104, v104, v128
	v_mul_f32_e32 v132, 0xbfb8aa3b, v120
	v_mul_f32_e32 v133, 0xbfb8aa3b, v104
	v_exp_f32_e32 v132, v132
	v_exp_f32_e32 v133, v133
	v_add_f32_e32 v132, 1.0, v132
	v_add_f32_e32 v133, 1.0, v133
	v_rcp_f32_e32 v132, v132
	v_rcp_f32_e32 v133, v133
	v_mul_f32_e32 v120, v120, v132
	v_mul_f32_e32 v104, v104, v133
	v_cvt_pk_bf16_f32 v134, v120, v104
	ds_write_b16 v197, v134 offset:4096
	ds_write_b16_d16_hi v197, v134 offset:4160
	v_mul_f32_e32 v88, v88, v128
	v_mul_f32_e32 v72, v72, v128
	v_mul_f32_e32 v136, 0xbfb8aa3b, v88
	v_mul_f32_e32 v137, 0xbfb8aa3b, v72
	v_exp_f32_e32 v136, v136
	v_exp_f32_e32 v137, v137
	v_add_f32_e32 v136, 1.0, v136
	v_add_f32_e32 v137, 1.0, v137
	v_rcp_f32_e32 v136, v136
	v_rcp_f32_e32 v137, v137
	v_mul_f32_e32 v88, v88, v136
	v_mul_f32_e32 v72, v72, v137
	v_cvt_pk_bf16_f32 v138, v88, v72
	ds_write_b16 v197, v138 offset:4224
	ds_write_b16_d16_hi v197, v138 offset:4288
	v_mul_f32_e32 v121, v121, v129
	v_mul_f32_e32 v105, v105, v129
	v_mul_f32_e32 v132, 0xbfb8aa3b, v121
	v_mul_f32_e32 v133, 0xbfb8aa3b, v105
	v_exp_f32_e32 v132, v132
	v_exp_f32_e32 v133, v133
	v_add_f32_e32 v132, 1.0, v132
	v_add_f32_e32 v133, 1.0, v133
	v_rcp_f32_e32 v132, v132
	v_rcp_f32_e32 v133, v133
	v_mul_f32_e32 v121, v121, v132
	v_mul_f32_e32 v105, v105, v133
	v_cvt_pk_bf16_f32 v134, v121, v105
	ds_write_b16 v197, v134 offset:4352
	ds_write_b16_d16_hi v197, v134 offset:4416
	v_mul_f32_e32 v89, v89, v129
	v_mul_f32_e32 v73, v73, v129
	v_mul_f32_e32 v136, 0xbfb8aa3b, v89
	v_mul_f32_e32 v137, 0xbfb8aa3b, v73
	v_exp_f32_e32 v136, v136
	v_exp_f32_e32 v137, v137
	v_add_f32_e32 v136, 1.0, v136
	v_add_f32_e32 v137, 1.0, v137
	v_rcp_f32_e32 v136, v136
	v_rcp_f32_e32 v137, v137
	v_mul_f32_e32 v89, v89, v136
	v_mul_f32_e32 v73, v73, v137
	v_cvt_pk_bf16_f32 v138, v89, v73
	ds_write_b16 v197, v138 offset:4480
	ds_write_b16_d16_hi v197, v138 offset:4544
	v_mul_f32_e32 v122, v122, v130
	v_mul_f32_e32 v106, v106, v130
	v_mul_f32_e32 v132, 0xbfb8aa3b, v122
	v_mul_f32_e32 v133, 0xbfb8aa3b, v106
	v_exp_f32_e32 v132, v132
	v_exp_f32_e32 v133, v133
	v_add_f32_e32 v132, 1.0, v132
	v_add_f32_e32 v133, 1.0, v133
	v_rcp_f32_e32 v132, v132
	v_rcp_f32_e32 v133, v133
	v_mul_f32_e32 v122, v122, v132
	v_mul_f32_e32 v106, v106, v133
	v_cvt_pk_bf16_f32 v134, v122, v106
	ds_write_b16 v197, v134 offset:4608
	ds_write_b16_d16_hi v197, v134 offset:4672
	v_mul_f32_e32 v90, v90, v130
	v_mul_f32_e32 v74, v74, v130
	v_mul_f32_e32 v136, 0xbfb8aa3b, v90
	v_mul_f32_e32 v137, 0xbfb8aa3b, v74
	v_exp_f32_e32 v136, v136
	v_exp_f32_e32 v137, v137
	v_add_f32_e32 v136, 1.0, v136
	v_add_f32_e32 v137, 1.0, v137
	v_rcp_f32_e32 v136, v136
	v_rcp_f32_e32 v137, v137
	v_mul_f32_e32 v90, v90, v136
	v_mul_f32_e32 v74, v74, v137
	v_cvt_pk_bf16_f32 v138, v90, v74
	ds_write_b16 v197, v138 offset:4736
	ds_write_b16_d16_hi v197, v138 offset:4800
	v_mul_f32_e32 v123, v123, v131
	v_mul_f32_e32 v107, v107, v131
	v_mul_f32_e32 v132, 0xbfb8aa3b, v123
	v_mul_f32_e32 v133, 0xbfb8aa3b, v107
	v_exp_f32_e32 v132, v132
	v_exp_f32_e32 v133, v133
	v_add_f32_e32 v132, 1.0, v132
	v_add_f32_e32 v133, 1.0, v133
	v_rcp_f32_e32 v132, v132
	v_rcp_f32_e32 v133, v133
	v_mul_f32_e32 v123, v123, v132
	v_mul_f32_e32 v107, v107, v133
	v_cvt_pk_bf16_f32 v134, v123, v107
	ds_write_b16 v197, v134 offset:4864
	ds_write_b16_d16_hi v197, v134 offset:4928
	v_mul_f32_e32 v91, v91, v131
	v_mul_f32_e32 v75, v75, v131
	v_mul_f32_e32 v136, 0xbfb8aa3b, v91
	v_mul_f32_e32 v137, 0xbfb8aa3b, v75
	v_exp_f32_e32 v136, v136
	v_exp_f32_e32 v137, v137
	v_add_f32_e32 v136, 1.0, v136
	v_add_f32_e32 v137, 1.0, v137
	v_rcp_f32_e32 v136, v136
	v_rcp_f32_e32 v137, v137
	v_mul_f32_e32 v91, v91, v136
	v_mul_f32_e32 v75, v75, v137
	v_cvt_pk_bf16_f32 v138, v91, v75
	ds_write_b16 v197, v138 offset:4992
	ds_write_b16_d16_hi v197, v138 offset:5056
	ds_read_b128 v[128:131], v196 offset:96
	s_waitcnt lgkmcnt(0)
	v_mul_f32_e32 v124, v124, v128
	v_mul_f32_e32 v108, v108, v128
	v_mul_f32_e32 v132, 0xbfb8aa3b, v124
	v_mul_f32_e32 v133, 0xbfb8aa3b, v108
	v_exp_f32_e32 v132, v132
	v_exp_f32_e32 v133, v133
	v_add_f32_e32 v132, 1.0, v132
	v_add_f32_e32 v133, 1.0, v133
	v_rcp_f32_e32 v132, v132
	v_rcp_f32_e32 v133, v133
	v_mul_f32_e32 v124, v124, v132
	v_mul_f32_e32 v108, v108, v133
	v_cvt_pk_bf16_f32 v134, v124, v108
	ds_write_b16 v197, v134 offset:6144
	ds_write_b16_d16_hi v197, v134 offset:6208
	v_mul_f32_e32 v92, v92, v128
	v_mul_f32_e32 v76, v76, v128
	v_mul_f32_e32 v136, 0xbfb8aa3b, v92
	v_mul_f32_e32 v137, 0xbfb8aa3b, v76
	v_exp_f32_e32 v136, v136
	v_exp_f32_e32 v137, v137
	v_add_f32_e32 v136, 1.0, v136
	v_add_f32_e32 v137, 1.0, v137
	v_rcp_f32_e32 v136, v136
	v_rcp_f32_e32 v137, v137
	v_mul_f32_e32 v92, v92, v136
	v_mul_f32_e32 v76, v76, v137
	v_cvt_pk_bf16_f32 v138, v92, v76
	ds_write_b16 v197, v138 offset:6272
	ds_write_b16_d16_hi v197, v138 offset:6336
	v_mul_f32_e32 v125, v125, v129
	v_mul_f32_e32 v109, v109, v129
	v_mul_f32_e32 v132, 0xbfb8aa3b, v125
	v_mul_f32_e32 v133, 0xbfb8aa3b, v109
	v_exp_f32_e32 v132, v132
	v_exp_f32_e32 v133, v133
	v_add_f32_e32 v132, 1.0, v132
	v_add_f32_e32 v133, 1.0, v133
	v_rcp_f32_e32 v132, v132
	v_rcp_f32_e32 v133, v133
	v_mul_f32_e32 v125, v125, v132
	v_mul_f32_e32 v109, v109, v133
	v_cvt_pk_bf16_f32 v134, v125, v109
	ds_write_b16 v197, v134 offset:6400
	ds_write_b16_d16_hi v197, v134 offset:6464
	v_mul_f32_e32 v93, v93, v129
	v_mul_f32_e32 v77, v77, v129
	v_mul_f32_e32 v136, 0xbfb8aa3b, v93
	v_mul_f32_e32 v137, 0xbfb8aa3b, v77
	v_exp_f32_e32 v136, v136
	v_exp_f32_e32 v137, v137
	v_add_f32_e32 v136, 1.0, v136
	v_add_f32_e32 v137, 1.0, v137
	v_rcp_f32_e32 v136, v136
; DI u16 f2bf(float a) { return (u16)(pack2(a, 0.f) & 0xffffu); }
; DI int crow(int reg, int g) { return (reg & 3) + 8 * (reg >> 2) + 4 * g; }
; DI float siluf(float x) { return x * __builtin_amdgcn_rcpf(1.f + __expf(-x)); }
; template <bool TR>
; DI void gemm_in_tile(const P& p, int l, int id, char* smem) {
;     ...
; #pragma unroll
;     for (int rb = 0; rb < 2; ++rb) {
; #pragma unroll
;       for (int reg = 0; reg < 16; ++reg) {
;         if ((reg & 7) == 0) asm volatile("" ::: "memory");
;         const int rl = 64 * wr + 32 * rb + crow(reg, g);
;         const int tok = m0 + rl;
;         const float rs = rs_s[rl];
; #pragma unroll
;         for (int cb = 0; cb < 4; ++cb) {
;           const int col = n0 - 3584 + 128 * wc + 32 * cb + li;
;           p.AG[(size_t)tok * 512 + col] = f2bf(siluf(acc[rb][cb][reg] * rs));
	v_rcp_f32_e32 v137, v137
	v_mul_f32_e32 v93, v93, v136
	v_mul_f32_e32 v77, v77, v137
	v_cvt_pk_bf16_f32 v138, v93, v77
	ds_write_b16 v197, v138 offset:6528
	ds_write_b16_d16_hi v197, v138 offset:6592
	v_mul_f32_e32 v126, v126, v130
	v_mul_f32_e32 v110, v110, v130
	v_mul_f32_e32 v132, 0xbfb8aa3b, v126
	v_mul_f32_e32 v133, 0xbfb8aa3b, v110
	v_exp_f32_e32 v132, v132
	v_exp_f32_e32 v133, v133
	v_add_f32_e32 v132, 1.0, v132
	v_add_f32_e32 v133, 1.0, v133
	v_rcp_f32_e32 v132, v132
	v_rcp_f32_e32 v133, v133
	v_mul_f32_e32 v126, v126, v132
	v_mul_f32_e32 v110, v110, v133
	v_cvt_pk_bf16_f32 v134, v126, v110
	ds_write_b16 v197, v134 offset:6656
	ds_write_b16_d16_hi v197, v134 offset:6720
	v_mul_f32_e32 v94, v94, v130
	v_mul_f32_e32 v78, v78, v130
	v_mul_f32_e32 v136, 0xbfb8aa3b, v94
	v_mul_f32_e32 v137, 0xbfb8aa3b, v78
	v_exp_f32_e32 v136, v136
	v_exp_f32_e32 v137, v137
	v_add_f32_e32 v136, 1.0, v136
	v_add_f32_e32 v137, 1.0, v137
	v_rcp_f32_e32 v136, v136
	v_rcp_f32_e32 v137, v137
	v_mul_f32_e32 v94, v94, v136
	v_mul_f32_e32 v78, v78, v137
	v_cvt_pk_bf16_f32 v138, v94, v78
	ds_write_b16 v197, v138 offset:6784
	ds_write_b16_d16_hi v197, v138 offset:6848
	v_mul_f32_e32 v127, v127, v131
	v_mul_f32_e32 v111, v111, v131
	v_mul_f32_e32 v132, 0xbfb8aa3b, v127
	v_mul_f32_e32 v133, 0xbfb8aa3b, v111
	v_exp_f32_e32 v132, v132
	v_exp_f32_e32 v133, v133
	v_add_f32_e32 v132, 1.0, v132
	v_add_f32_e32 v133, 1.0, v133
	v_rcp_f32_e32 v132, v132
	v_rcp_f32_e32 v133, v133
	v_mul_f32_e32 v127, v127, v132
	v_mul_f32_e32 v111, v111, v133
	v_cvt_pk_bf16_f32 v134, v127, v111
	ds_write_b16 v197, v134 offset:6912
	ds_write_b16_d16_hi v197, v134 offset:6976
	v_mul_f32_e32 v95, v95, v131
	v_mul_f32_e32 v79, v79, v131
	v_mul_f32_e32 v136, 0xbfb8aa3b, v95
	v_mul_f32_e32 v137, 0xbfb8aa3b, v79
	v_exp_f32_e32 v136, v136
	v_exp_f32_e32 v137, v137
	v_add_f32_e32 v136, 1.0, v136
	v_add_f32_e32 v137, 1.0, v137
	v_rcp_f32_e32 v136, v136
	v_rcp_f32_e32 v137, v137
	v_mul_f32_e32 v95, v95, v136
	v_mul_f32_e32 v79, v79, v137
	v_cvt_pk_bf16_f32 v138, v95, v79
	ds_write_b16 v197, v138 offset:7040
	ds_write_b16_d16_hi v197, v138 offset:7104
	ds_read_b128 v[128:131], v196 offset:128
	s_waitcnt lgkmcnt(0)
	v_mul_f32_e32 v48, v48, v128
	v_mul_f32_e32 v32, v32, v128
	v_mul_f32_e32 v132, 0xbfb8aa3b, v48
	v_mul_f32_e32 v133, 0xbfb8aa3b, v32
	v_exp_f32_e32 v132, v132
	v_exp_f32_e32 v133, v133
	v_add_f32_e32 v132, 1.0, v132
	v_add_f32_e32 v133, 1.0, v133
	v_rcp_f32_e32 v132, v132
	v_rcp_f32_e32 v133, v133
	v_mul_f32_e32 v48, v48, v132
	v_mul_f32_e32 v32, v32, v133
	v_cvt_pk_bf16_f32 v134, v48, v32
	ds_write_b16 v197, v134 offset:8192
	ds_write_b16_d16_hi v197, v134 offset:8256
	v_mul_f32_e32 v16, v16, v128
	v_mul_f32_e32 v0, v0, v128
	v_mul_f32_e32 v136, 0xbfb8aa3b, v16
	v_mul_f32_e32 v137, 0xbfb8aa3b, v0
	v_exp_f32_e32 v136, v136
	v_exp_f32_e32 v137, v137
	v_add_f32_e32 v136, 1.0, v136
	v_add_f32_e32 v137, 1.0, v137
	v_rcp_f32_e32 v136, v136
	v_rcp_f32_e32 v137, v137
	v_mul_f32_e32 v16, v16, v136
	v_mul_f32_e32 v0, v0, v137
	v_cvt_pk_bf16_f32 v138, v16, v0
	ds_write_b16 v197, v138 offset:8320
	ds_write_b16_d16_hi v197, v138 offset:8384
	v_mul_f32_e32 v49, v49, v129
	v_mul_f32_e32 v33, v33, v129
	v_mul_f32_e32 v132, 0xbfb8aa3b, v49
	v_mul_f32_e32 v133, 0xbfb8aa3b, v33
	v_exp_f32_e32 v132, v132
	v_exp_f32_e32 v133, v133
	v_add_f32_e32 v132, 1.0, v132
	v_add_f32_e32 v133, 1.0, v133
	v_rcp_f32_e32 v132, v132
	v_rcp_f32_e32 v133, v133
	v_mul_f32_e32 v49, v49, v132
	v_mul_f32_e32 v33, v33, v133
	v_cvt_pk_bf16_f32 v134, v49, v33
	ds_write_b16 v197, v134 offset:8448
	ds_write_b16_d16_hi v197, v134 offset:8512
	v_mul_f32_e32 v17, v17, v129
	v_mul_f32_e32 v1, v1, v129
	v_mul_f32_e32 v136, 0xbfb8aa3b, v17
	v_mul_f32_e32 v137, 0xbfb8aa3b, v1
	v_exp_f32_e32 v136, v136
	v_exp_f32_e32 v137, v137
	v_add_f32_e32 v136, 1.0, v136
	v_add_f32_e32 v137, 1.0, v137
	v_rcp_f32_e32 v136, v136
	v_rcp_f32_e32 v137, v137
	v_mul_f32_e32 v17, v17, v136
	v_mul_f32_e32 v1, v1, v137
	v_cvt_pk_bf16_f32 v138, v17, v1
	ds_write_b16 v197, v138 offset:8576
	ds_write_b16_d16_hi v197, v138 offset:8640
	v_mul_f32_e32 v50, v50, v130
	v_mul_f32_e32 v34, v34, v130
	v_mul_f32_e32 v132, 0xbfb8aa3b, v50
	v_mul_f32_e32 v133, 0xbfb8aa3b, v34
	v_exp_f32_e32 v132, v132
	v_exp_f32_e32 v133, v133
	v_add_f32_e32 v132, 1.0, v132
	v_add_f32_e32 v133, 1.0, v133
	v_rcp_f32_e32 v132, v132
	v_rcp_f32_e32 v133, v133
	v_mul_f32_e32 v50, v50, v132
	v_mul_f32_e32 v34, v34, v133
	v_cvt_pk_bf16_f32 v134, v50, v34
	ds_write_b16 v197, v134 offset:8704
	ds_write_b16_d16_hi v197, v134 offset:8768
	v_mul_f32_e32 v18, v18, v130
	v_mul_f32_e32 v2, v2, v130
	v_mul_f32_e32 v136, 0xbfb8aa3b, v18
	v_mul_f32_e32 v137, 0xbfb8aa3b, v2
	v_exp_f32_e32 v136, v136
	v_exp_f32_e32 v137, v137
	v_add_f32_e32 v136, 1.0, v136
	v_add_f32_e32 v137, 1.0, v137
	v_rcp_f32_e32 v136, v136
	v_rcp_f32_e32 v137, v137
	v_mul_f32_e32 v18, v18, v136
	v_mul_f32_e32 v2, v2, v137
	v_cvt_pk_bf16_f32 v138, v18, v2
	ds_write_b16 v197, v138 offset:8832
	ds_write_b16_d16_hi v197, v138 offset:8896
	v_mul_f32_e32 v51, v51, v131
	v_mul_f32_e32 v35, v35, v131
	v_mul_f32_e32 v132, 0xbfb8aa3b, v51
	v_mul_f32_e32 v133, 0xbfb8aa3b, v35
	v_exp_f32_e32 v132, v132
	v_exp_f32_e32 v133, v133
	v_add_f32_e32 v132, 1.0, v132
	v_add_f32_e32 v133, 1.0, v133
	v_rcp_f32_e32 v132, v132
	v_rcp_f32_e32 v133, v133
	v_mul_f32_e32 v51, v51, v132
	v_mul_f32_e32 v35, v35, v133
	v_cvt_pk_bf16_f32 v134, v51, v35
	ds_write_b16 v197, v134 offset:8960
	ds_write_b16_d16_hi v197, v134 offset:9024
	v_mul_f32_e32 v19, v19, v131
	v_mul_f32_e32 v3, v3, v131
	v_mul_f32_e32 v136, 0xbfb8aa3b, v19
	v_mul_f32_e32 v137, 0xbfb8aa3b, v3
	v_exp_f32_e32 v136, v136
	v_exp_f32_e32 v137, v137
	v_add_f32_e32 v136, 1.0, v136
	v_add_f32_e32 v137, 1.0, v137
	v_rcp_f32_e32 v136, v136
	v_rcp_f32_e32 v137, v137
	v_mul_f32_e32 v19, v19, v136
	v_mul_f32_e32 v3, v3, v137
	v_cvt_pk_bf16_f32 v138, v19, v3
	ds_write_b16 v197, v138 offset:9088
	ds_write_b16_d16_hi v197, v138 offset:9152
	ds_read_b128 v[128:131], v196 offset:160
	s_waitcnt lgkmcnt(0)
; DI u16 f2bf(float a) { return (u16)(pack2(a, 0.f) & 0xffffu); }
; DI int crow(int reg, int g) { return (reg & 3) + 8 * (reg >> 2) + 4 * g; }
; DI float siluf(float x) { return x * __builtin_amdgcn_rcpf(1.f + __expf(-x)); }
; template <bool TR>
; DI void gemm_in_tile(const P& p, int l, int id, char* smem) {
;     ...
; #pragma unroll
;     for (int rb = 0; rb < 2; ++rb) {
; #pragma unroll
;       for (int reg = 0; reg < 16; ++reg) {
;         if ((reg & 7) == 0) asm volatile("" ::: "memory");
;         const int rl = 64 * wr + 32 * rb + crow(reg, g);
;         const int tok = m0 + rl;
;         const float rs = rs_s[rl];
; #pragma unroll
;         for (int cb = 0; cb < 4; ++cb) {
;           const int col = n0 - 3584 + 128 * wc + 32 * cb + li;
;           p.AG[(size_t)tok * 512 + col] = f2bf(siluf(acc[rb][cb][reg] * rs));
	v_mul_f32_e32 v52, v52, v128
	v_mul_f32_e32 v36, v36, v128
	v_mul_f32_e32 v132, 0xbfb8aa3b, v52
	v_mul_f32_e32 v133, 0xbfb8aa3b, v36
	v_exp_f32_e32 v132, v132
	v_exp_f32_e32 v133, v133
	v_add_f32_e32 v132, 1.0, v132
	v_add_f32_e32 v133, 1.0, v133
	v_rcp_f32_e32 v132, v132
	v_rcp_f32_e32 v133, v133
	v_mul_f32_e32 v52, v52, v132
	v_mul_f32_e32 v36, v36, v133
	v_cvt_pk_bf16_f32 v134, v52, v36
	ds_write_b16 v197, v134 offset:10240
	ds_write_b16_d16_hi v197, v134 offset:10304
	v_mul_f32_e32 v20, v20, v128
	v_mul_f32_e32 v4, v4, v128
	v_mul_f32_e32 v136, 0xbfb8aa3b, v20
	v_mul_f32_e32 v137, 0xbfb8aa3b, v4
	v_exp_f32_e32 v136, v136
	v_exp_f32_e32 v137, v137
	v_add_f32_e32 v136, 1.0, v136
	v_add_f32_e32 v137, 1.0, v137
	v_rcp_f32_e32 v136, v136
	v_rcp_f32_e32 v137, v137
	v_mul_f32_e32 v20, v20, v136
	v_mul_f32_e32 v4, v4, v137
	v_cvt_pk_bf16_f32 v138, v20, v4
	ds_write_b16 v197, v138 offset:10368
	ds_write_b16_d16_hi v197, v138 offset:10432
	v_mul_f32_e32 v53, v53, v129
	v_mul_f32_e32 v37, v37, v129
	v_mul_f32_e32 v132, 0xbfb8aa3b, v53
	v_mul_f32_e32 v133, 0xbfb8aa3b, v37
	v_exp_f32_e32 v132, v132
	v_exp_f32_e32 v133, v133
	v_add_f32_e32 v132, 1.0, v132
	v_add_f32_e32 v133, 1.0, v133
	v_rcp_f32_e32 v132, v132
	v_rcp_f32_e32 v133, v133
	v_mul_f32_e32 v53, v53, v132
	v_mul_f32_e32 v37, v37, v133
	v_cvt_pk_bf16_f32 v134, v53, v37
	ds_write_b16 v197, v134 offset:10496
	ds_write_b16_d16_hi v197, v134 offset:10560
	v_mul_f32_e32 v21, v21, v129
	v_mul_f32_e32 v5, v5, v129
	v_mul_f32_e32 v136, 0xbfb8aa3b, v21
	v_mul_f32_e32 v137, 0xbfb8aa3b, v5
	v_exp_f32_e32 v136, v136
	v_exp_f32_e32 v137, v137
	v_add_f32_e32 v136, 1.0, v136
	v_add_f32_e32 v137, 1.0, v137
	v_rcp_f32_e32 v136, v136
	v_rcp_f32_e32 v137, v137
	v_mul_f32_e32 v21, v21, v136
	v_mul_f32_e32 v5, v5, v137
	v_cvt_pk_bf16_f32 v138, v21, v5
	ds_write_b16 v197, v138 offset:10624
	ds_write_b16_d16_hi v197, v138 offset:10688
	v_mul_f32_e32 v54, v54, v130
	v_mul_f32_e32 v38, v38, v130
	v_mul_f32_e32 v132, 0xbfb8aa3b, v54
	v_mul_f32_e32 v133, 0xbfb8aa3b, v38
	v_exp_f32_e32 v132, v132
	v_exp_f32_e32 v133, v133
	v_add_f32_e32 v132, 1.0, v132
	v_add_f32_e32 v133, 1.0, v133
	v_rcp_f32_e32 v132, v132
	v_rcp_f32_e32 v133, v133
	v_mul_f32_e32 v54, v54, v132
	v_mul_f32_e32 v38, v38, v133
	v_cvt_pk_bf16_f32 v134, v54, v38
	ds_write_b16 v197, v134 offset:10752
	ds_write_b16_d16_hi v197, v134 offset:10816
	v_mul_f32_e32 v22, v22, v130
	v_mul_f32_e32 v6, v6, v130
	v_mul_f32_e32 v136, 0xbfb8aa3b, v22
	v_mul_f32_e32 v137, 0xbfb8aa3b, v6
	v_exp_f32_e32 v136, v136
	v_exp_f32_e32 v137, v137
	v_add_f32_e32 v136, 1.0, v136
	v_add_f32_e32 v137, 1.0, v137
	v_rcp_f32_e32 v136, v136
	v_rcp_f32_e32 v137, v137
	v_mul_f32_e32 v22, v22, v136
	v_mul_f32_e32 v6, v6, v137
	v_cvt_pk_bf16_f32 v138, v22, v6
	ds_write_b16 v197, v138 offset:10880
	ds_write_b16_d16_hi v197, v138 offset:10944
	v_mul_f32_e32 v55, v55, v131
	v_mul_f32_e32 v39, v39, v131
	v_mul_f32_e32 v132, 0xbfb8aa3b, v55
	v_mul_f32_e32 v133, 0xbfb8aa3b, v39
	v_exp_f32_e32 v132, v132
	v_exp_f32_e32 v133, v133
	v_add_f32_e32 v132, 1.0, v132
	v_add_f32_e32 v133, 1.0, v133
	v_rcp_f32_e32 v132, v132
	v_rcp_f32_e32 v133, v133
	v_mul_f32_e32 v55, v55, v132
	v_mul_f32_e32 v39, v39, v133
	v_cvt_pk_bf16_f32 v134, v55, v39
	ds_write_b16 v197, v134 offset:11008
	ds_write_b16_d16_hi v197, v134 offset:11072
	v_mul_f32_e32 v23, v23, v131
	v_mul_f32_e32 v7, v7, v131
	v_mul_f32_e32 v136, 0xbfb8aa3b, v23
	v_mul_f32_e32 v137, 0xbfb8aa3b, v7
	v_exp_f32_e32 v136, v136
	v_exp_f32_e32 v137, v137
	v_add_f32_e32 v136, 1.0, v136
	v_add_f32_e32 v137, 1.0, v137
	v_rcp_f32_e32 v136, v136
	v_rcp_f32_e32 v137, v137
	v_mul_f32_e32 v23, v23, v136
	v_mul_f32_e32 v7, v7, v137
	v_cvt_pk_bf16_f32 v138, v23, v7
	ds_write_b16 v197, v138 offset:11136
	ds_write_b16_d16_hi v197, v138 offset:11200
	ds_read_b128 v[128:131], v196 offset:192
	s_waitcnt lgkmcnt(0)
	v_mul_f32_e32 v56, v56, v128
	v_mul_f32_e32 v40, v40, v128
	v_mul_f32_e32 v132, 0xbfb8aa3b, v56
	v_mul_f32_e32 v133, 0xbfb8aa3b, v40
	v_exp_f32_e32 v132, v132
	v_exp_f32_e32 v133, v133
	v_add_f32_e32 v132, 1.0, v132
	v_add_f32_e32 v133, 1.0, v133
	v_rcp_f32_e32 v132, v132
	v_rcp_f32_e32 v133, v133
	v_mul_f32_e32 v56, v56, v132
	v_mul_f32_e32 v40, v40, v133
	v_cvt_pk_bf16_f32 v134, v56, v40
	ds_write_b16 v197, v134 offset:12288
	ds_write_b16_d16_hi v197, v134 offset:12352
	v_mul_f32_e32 v24, v24, v128
	v_mul_f32_e32 v8, v8, v128
	v_mul_f32_e32 v136, 0xbfb8aa3b, v24
	v_mul_f32_e32 v137, 0xbfb8aa3b, v8
	v_exp_f32_e32 v136, v136
	v_exp_f32_e32 v137, v137
	v_add_f32_e32 v136, 1.0, v136
	v_add_f32_e32 v137, 1.0, v137
	v_rcp_f32_e32 v136, v136
	v_rcp_f32_e32 v137, v137
	v_mul_f32_e32 v24, v24, v136
	v_mul_f32_e32 v8, v8, v137
	v_cvt_pk_bf16_f32 v138, v24, v8
	ds_write_b16 v197, v138 offset:12416
	ds_write_b16_d16_hi v197, v138 offset:12480
	v_mul_f32_e32 v57, v57, v129
	v_mul_f32_e32 v41, v41, v129
	v_mul_f32_e32 v132, 0xbfb8aa3b, v57
	v_mul_f32_e32 v133, 0xbfb8aa3b, v41
	v_exp_f32_e32 v132, v132
	v_exp_f32_e32 v133, v133
	v_add_f32_e32 v132, 1.0, v132
	v_add_f32_e32 v133, 1.0, v133
	v_rcp_f32_e32 v132, v132
	v_rcp_f32_e32 v133, v133
	v_mul_f32_e32 v57, v57, v132
	v_mul_f32_e32 v41, v41, v133
	v_cvt_pk_bf16_f32 v134, v57, v41
	ds_write_b16 v197, v134 offset:12544
	ds_write_b16_d16_hi v197, v134 offset:12608
	v_mul_f32_e32 v25, v25, v129
	v_mul_f32_e32 v9, v9, v129
	v_mul_f32_e32 v136, 0xbfb8aa3b, v25
	v_mul_f32_e32 v137, 0xbfb8aa3b, v9
	v_exp_f32_e32 v136, v136
	v_exp_f32_e32 v137, v137
	v_add_f32_e32 v136, 1.0, v136
	v_add_f32_e32 v137, 1.0, v137
	v_rcp_f32_e32 v136, v136
	v_rcp_f32_e32 v137, v137
	v_mul_f32_e32 v25, v25, v136
	v_mul_f32_e32 v9, v9, v137
; DI u16 f2bf(float a) { return (u16)(pack2(a, 0.f) & 0xffffu); }
; DI int crow(int reg, int g) { return (reg & 3) + 8 * (reg >> 2) + 4 * g; }
; DI float siluf(float x) { return x * __builtin_amdgcn_rcpf(1.f + __expf(-x)); }
; template <bool TR>
; DI void gemm_in_tile(const P& p, int l, int id, char* smem) {
;     ...
; #pragma unroll
;     for (int rb = 0; rb < 2; ++rb) {
; #pragma unroll
;       for (int reg = 0; reg < 16; ++reg) {
;         if ((reg & 7) == 0) asm volatile("" ::: "memory");
;         const int rl = 64 * wr + 32 * rb + crow(reg, g);
;         const int tok = m0 + rl;
;         const float rs = rs_s[rl];
; #pragma unroll
;         for (int cb = 0; cb < 4; ++cb) {
;           const int col = n0 - 3584 + 128 * wc + 32 * cb + li;
;           p.AG[(size_t)tok * 512 + col] = f2bf(siluf(acc[rb][cb][reg] * rs));
;         }
;       }
;     }
	v_cvt_pk_bf16_f32 v138, v25, v9
	ds_write_b16 v197, v138 offset:12672
	ds_write_b16_d16_hi v197, v138 offset:12736
	v_mul_f32_e32 v58, v58, v130
	v_mul_f32_e32 v42, v42, v130
	v_mul_f32_e32 v132, 0xbfb8aa3b, v58
	v_mul_f32_e32 v133, 0xbfb8aa3b, v42
	v_exp_f32_e32 v132, v132
	v_exp_f32_e32 v133, v133
	v_add_f32_e32 v132, 1.0, v132
	v_add_f32_e32 v133, 1.0, v133
	v_rcp_f32_e32 v132, v132
	v_rcp_f32_e32 v133, v133
	v_mul_f32_e32 v58, v58, v132
	v_mul_f32_e32 v42, v42, v133
	v_cvt_pk_bf16_f32 v134, v58, v42
	ds_write_b16 v197, v134 offset:12800
	ds_write_b16_d16_hi v197, v134 offset:12864
	v_mul_f32_e32 v26, v26, v130
	v_mul_f32_e32 v10, v10, v130
	v_mul_f32_e32 v136, 0xbfb8aa3b, v26
	v_mul_f32_e32 v137, 0xbfb8aa3b, v10
	v_exp_f32_e32 v136, v136
	v_exp_f32_e32 v137, v137
	v_add_f32_e32 v136, 1.0, v136
	v_add_f32_e32 v137, 1.0, v137
	v_rcp_f32_e32 v136, v136
	v_rcp_f32_e32 v137, v137
	v_mul_f32_e32 v26, v26, v136
	v_mul_f32_e32 v10, v10, v137
	v_cvt_pk_bf16_f32 v138, v26, v10
	ds_write_b16 v197, v138 offset:12928
	ds_write_b16_d16_hi v197, v138 offset:12992
	v_mul_f32_e32 v59, v59, v131
	v_mul_f32_e32 v43, v43, v131
	v_mul_f32_e32 v132, 0xbfb8aa3b, v59
	v_mul_f32_e32 v133, 0xbfb8aa3b, v43
	v_exp_f32_e32 v132, v132
	v_exp_f32_e32 v133, v133
	v_add_f32_e32 v132, 1.0, v132
	v_add_f32_e32 v133, 1.0, v133
	v_rcp_f32_e32 v132, v132
	v_rcp_f32_e32 v133, v133
	v_mul_f32_e32 v59, v59, v132
	v_mul_f32_e32 v43, v43, v133
	v_cvt_pk_bf16_f32 v134, v59, v43
	ds_write_b16 v197, v134 offset:13056
	ds_write_b16_d16_hi v197, v134 offset:13120
	v_mul_f32_e32 v27, v27, v131
	v_mul_f32_e32 v11, v11, v131
	v_mul_f32_e32 v136, 0xbfb8aa3b, v27
	v_mul_f32_e32 v137, 0xbfb8aa3b, v11
	v_exp_f32_e32 v136, v136
	v_exp_f32_e32 v137, v137
	v_add_f32_e32 v136, 1.0, v136
	v_add_f32_e32 v137, 1.0, v137
	v_rcp_f32_e32 v136, v136
	v_rcp_f32_e32 v137, v137
	v_mul_f32_e32 v27, v27, v136
	v_mul_f32_e32 v11, v11, v137
	v_cvt_pk_bf16_f32 v138, v27, v11
	ds_write_b16 v197, v138 offset:13184
	ds_write_b16_d16_hi v197, v138 offset:13248
	ds_read_b128 v[128:131], v196 offset:224
	s_waitcnt lgkmcnt(0)
	v_mul_f32_e32 v60, v60, v128
	v_mul_f32_e32 v44, v44, v128
	v_mul_f32_e32 v132, 0xbfb8aa3b, v60
	v_mul_f32_e32 v133, 0xbfb8aa3b, v44
	v_exp_f32_e32 v132, v132
	v_exp_f32_e32 v133, v133
	v_add_f32_e32 v132, 1.0, v132
	v_add_f32_e32 v133, 1.0, v133
	v_rcp_f32_e32 v132, v132
	v_rcp_f32_e32 v133, v133
	v_mul_f32_e32 v60, v60, v132
	v_mul_f32_e32 v44, v44, v133
	v_cvt_pk_bf16_f32 v134, v60, v44
	ds_write_b16 v197, v134 offset:14336
	ds_write_b16_d16_hi v197, v134 offset:14400
	v_mul_f32_e32 v28, v28, v128
	v_mul_f32_e32 v12, v12, v128
	v_mul_f32_e32 v136, 0xbfb8aa3b, v28
	v_mul_f32_e32 v137, 0xbfb8aa3b, v12
	v_exp_f32_e32 v136, v136
	v_exp_f32_e32 v137, v137
	v_add_f32_e32 v136, 1.0, v136
	v_add_f32_e32 v137, 1.0, v137
	v_rcp_f32_e32 v136, v136
	v_rcp_f32_e32 v137, v137
	v_mul_f32_e32 v28, v28, v136
	v_mul_f32_e32 v12, v12, v137
	v_cvt_pk_bf16_f32 v138, v28, v12
	ds_write_b16 v197, v138 offset:14464
	ds_write_b16_d16_hi v197, v138 offset:14528
	v_mul_f32_e32 v61, v61, v129
	v_mul_f32_e32 v45, v45, v129
	v_mul_f32_e32 v132, 0xbfb8aa3b, v61
	v_mul_f32_e32 v133, 0xbfb8aa3b, v45
	v_exp_f32_e32 v132, v132
	v_exp_f32_e32 v133, v133
	v_add_f32_e32 v132, 1.0, v132
	v_add_f32_e32 v133, 1.0, v133
	v_rcp_f32_e32 v132, v132
	v_rcp_f32_e32 v133, v133
	v_mul_f32_e32 v61, v61, v132
	v_mul_f32_e32 v45, v45, v133
	v_cvt_pk_bf16_f32 v134, v61, v45
	ds_write_b16 v197, v134 offset:14592
	ds_write_b16_d16_hi v197, v134 offset:14656
	v_mul_f32_e32 v29, v29, v129
	v_mul_f32_e32 v13, v13, v129
	v_mul_f32_e32 v136, 0xbfb8aa3b, v29
	v_mul_f32_e32 v137, 0xbfb8aa3b, v13
	v_exp_f32_e32 v136, v136
	v_exp_f32_e32 v137, v137
	v_add_f32_e32 v136, 1.0, v136
	v_add_f32_e32 v137, 1.0, v137
	v_rcp_f32_e32 v136, v136
	v_rcp_f32_e32 v137, v137
	v_mul_f32_e32 v29, v29, v136
	v_mul_f32_e32 v13, v13, v137
	v_cvt_pk_bf16_f32 v138, v29, v13
	ds_write_b16 v197, v138 offset:14720
	ds_write_b16_d16_hi v197, v138 offset:14784
	v_mul_f32_e32 v62, v62, v130
	v_mul_f32_e32 v46, v46, v130
	v_mul_f32_e32 v132, 0xbfb8aa3b, v62
	v_mul_f32_e32 v133, 0xbfb8aa3b, v46
	v_exp_f32_e32 v132, v132
	v_exp_f32_e32 v133, v133
	v_add_f32_e32 v132, 1.0, v132
	v_add_f32_e32 v133, 1.0, v133
	v_rcp_f32_e32 v132, v132
	v_rcp_f32_e32 v133, v133
	v_mul_f32_e32 v62, v62, v132
	v_mul_f32_e32 v46, v46, v133
	v_cvt_pk_bf16_f32 v134, v62, v46
	ds_write_b16 v197, v134 offset:14848
	ds_write_b16_d16_hi v197, v134 offset:14912
	v_mul_f32_e32 v30, v30, v130
	v_mul_f32_e32 v14, v14, v130
	v_mul_f32_e32 v136, 0xbfb8aa3b, v30
	v_mul_f32_e32 v137, 0xbfb8aa3b, v14
	v_exp_f32_e32 v136, v136
	v_exp_f32_e32 v137, v137
	v_add_f32_e32 v136, 1.0, v136
	v_add_f32_e32 v137, 1.0, v137
	v_rcp_f32_e32 v136, v136
	v_rcp_f32_e32 v137, v137
	v_mul_f32_e32 v30, v30, v136
	v_mul_f32_e32 v14, v14, v137
	v_cvt_pk_bf16_f32 v138, v30, v14
	ds_write_b16 v197, v138 offset:14976
	ds_write_b16_d16_hi v197, v138 offset:15040
	v_mul_f32_e32 v63, v63, v131
	v_mul_f32_e32 v47, v47, v131
	v_mul_f32_e32 v132, 0xbfb8aa3b, v63
	v_mul_f32_e32 v133, 0xbfb8aa3b, v47
	v_exp_f32_e32 v132, v132
	v_exp_f32_e32 v133, v133
	v_add_f32_e32 v132, 1.0, v132
	v_add_f32_e32 v133, 1.0, v133
	v_rcp_f32_e32 v132, v132
	v_rcp_f32_e32 v133, v133
	v_mul_f32_e32 v63, v63, v132
	v_mul_f32_e32 v47, v47, v133
	v_cvt_pk_bf16_f32 v134, v63, v47
	ds_write_b16 v197, v134 offset:15104
	ds_write_b16_d16_hi v197, v134 offset:15168
	v_mul_f32_e32 v31, v31, v131
	v_mul_f32_e32 v15, v15, v131
	v_mul_f32_e32 v136, 0xbfb8aa3b, v31
	v_mul_f32_e32 v137, 0xbfb8aa3b, v15
	v_exp_f32_e32 v136, v136
	v_exp_f32_e32 v137, v137
	v_add_f32_e32 v136, 1.0, v136
	v_add_f32_e32 v137, 1.0, v137
	v_rcp_f32_e32 v136, v136
	v_rcp_f32_e32 v137, v137
	v_mul_f32_e32 v31, v31, v136
	v_mul_f32_e32 v15, v15, v137
	v_cvt_pk_bf16_f32 v138, v31, v15
	ds_write_b16 v197, v138 offset:15232
	ds_write_b16_d16_hi v197, v138 offset:15296
	s_waitcnt lgkmcnt(0)
; DI u16 f2bf(float a) { return (u16)(pack2(a, 0.f) & 0xffffu); }
; DI float siluf(float x) { return x * __builtin_amdgcn_rcpf(1.f + __expf(-x)); }
; template <bool TR>
; DI void gemm_in_tile(const P& p, int l, int id, char* smem) {
;     ...
;         for (int cb = 0; cb < 4; ++cb) {
;           const int col = n0 - 3584 + 128 * wc + 32 * cb + li;
;           p.AG[(size_t)tok * 512 + col] = f2bf(siluf(acc[rb][cb][reg] * rs));
;         }
	ds_read_b128 v[8:11], v249 offset:0
	ds_read_b128 v[12:15], v249 offset:1024
	ds_read_b128 v[16:19], v249 offset:2048
	ds_read_b128 v[20:23], v249 offset:3072
	ds_read_b128 v[24:27], v249 offset:4096
	ds_read_b128 v[28:31], v249 offset:5120
	ds_read_b128 v[32:35], v249 offset:6144
	ds_read_b128 v[36:39], v249 offset:7168
	ds_read_b128 v[40:43], v249 offset:8192
	ds_read_b128 v[44:47], v249 offset:9216
	ds_read_b128 v[48:51], v249 offset:10240
	ds_read_b128 v[52:55], v249 offset:11264
	ds_read_b128 v[56:59], v249 offset:12288
	ds_read_b128 v[60:63], v249 offset:13312
	ds_read_b128 v[64:67], v249 offset:14336
	ds_read_b128 v[68:71], v249 offset:15360
	s_waitcnt lgkmcnt(15)
	global_store_dwordx4 v250, v[8:11], s[30:31]
	v_add_u32_e32 v250, 0x1000, v250
	s_waitcnt lgkmcnt(14)
	global_store_dwordx4 v250, v[12:15], s[30:31]
	v_add_u32_e32 v250, 0x1000, v250
	s_waitcnt lgkmcnt(13)
	global_store_dwordx4 v250, v[16:19], s[30:31]
	v_add_u32_e32 v250, 0x1000, v250
	s_waitcnt lgkmcnt(12)
	global_store_dwordx4 v250, v[20:23], s[30:31]
	v_add_u32_e32 v250, 0x1000, v250
	s_waitcnt lgkmcnt(11)
	global_store_dwordx4 v250, v[24:27], s[30:31]
	v_add_u32_e32 v250, 0x1000, v250
	s_waitcnt lgkmcnt(10)
	global_store_dwordx4 v250, v[28:31], s[30:31]
	v_add_u32_e32 v250, 0x1000, v250
	s_waitcnt lgkmcnt(9)
	global_store_dwordx4 v250, v[32:35], s[30:31]
	v_add_u32_e32 v250, 0x1000, v250
	s_waitcnt lgkmcnt(8)
	global_store_dwordx4 v250, v[36:39], s[30:31]
	v_add_u32_e32 v250, 0x1000, v250
	s_waitcnt lgkmcnt(7)
	global_store_dwordx4 v250, v[40:43], s[30:31]
	v_add_u32_e32 v250, 0x1000, v250
	s_waitcnt lgkmcnt(6)
	global_store_dwordx4 v250, v[44:47], s[30:31]
	v_add_u32_e32 v250, 0x1000, v250
	s_waitcnt lgkmcnt(5)
	global_store_dwordx4 v250, v[48:51], s[30:31]
	v_add_u32_e32 v250, 0x1000, v250
	s_waitcnt lgkmcnt(4)
	global_store_dwordx4 v250, v[52:55], s[30:31]
	v_add_u32_e32 v250, 0x1000, v250
	s_waitcnt lgkmcnt(3)
	global_store_dwordx4 v250, v[56:59], s[30:31]
	v_add_u32_e32 v250, 0x1000, v250
	s_waitcnt lgkmcnt(2)
	global_store_dwordx4 v250, v[60:63], s[30:31]
	v_add_u32_e32 v250, 0x1000, v250
	s_waitcnt lgkmcnt(1)
	global_store_dwordx4 v250, v[64:67], s[30:31]
	v_add_u32_e32 v250, 0x1000, v250
	s_waitcnt lgkmcnt(0)
	global_store_dwordx4 v250, v[68:71], s[30:31]
	s_branch .LBB0_337
